# attention: K/V tile t+2 global loads hoisted to loop top; QK batch-B lgkmcnt wait moved to 9th MFMA
# speedup vs baseline: 1.0075x; 1.0075x over previous
;     __device__ bool next(int i, Unit& u) const { const int L = i * G + c; if (L >= 256) return false; u.g = L >> 6; const int r = L & 63; u.pm = r >> 1; u.pn = r & 1; return true; }
;     __device__ bool next(int i, Unit& u) const {
;         const long L = (long)i * G + c; if (L >= nwg) return false;
;         int wgid = (int)L; { const int q = nwg / NXCD, r = nwg % NXCD, xcd = wgid % NXCD, off = wgid / NXCD; wgid = (xcd < r ? xcd * (q + 1) : r * (q + 1) + (xcd - r) * q) + off; }
;         const int nig = WGM * nN, gid = wgid / nig, fm = gid * WGM, gsz = (nM - fm) < WGM ? (nM - fm) : WGM;
;         u.pm = fm + ((wgid % nig) % gsz); u.pn = (wgid % nig) / gsz; u.g = 0; return true;
; __global__ void __launch_bounds__(512, 2) mk_fwd(Args args) {
;     ...
;     if (IN(3)) {
;         pg8::Gemm g{actb, ws + WS_WIN, DM, 2}; pg8::StaticOrder S; S.init(M, NINP, F.G, (int)blockIdx.x);
;         EpiWin E{(bf16_t*)(ws + WS_Q), (bf16_t*)(ws + WS_KV), (float*)(ws + WS_U), (float*)(ws + WS_GATES), racc1, KV_STRIDE_B / 2};
;         pg8::gemm_phase(F.lds, g, S, E);
.LBB0_1470:
	s_cmp_lt_i32 s4, 4
	s_cselect_b64 s[0:1], -1, 0
	s_cmp_gt_i32 s5, 3
	s_cselect_b64 s[2:3], -1, 0
	s_and_b64 s[0:1], s[0:1], s[2:3]
	s_andn2_b64 vcc, exec, s[0:1]
	s_cbranch_vccnz .LBB0_2422
	s_cmpk_lt_i32 s69, 0x3a0
	s_cselect_b64 s[2:3], -1, 0
	s_cmpk_gt_i32 s69, 0x39f
	v_readfirstlane_b32 s4, v0
	s_cbranch_scc1 .LBB0_1473
	s_ashr_i32 s0, s69, 31
	s_lshr_b32 s0, s0, 29
	s_add_i32 s0, s69, s0
	s_ashr_i32 s1, s0, 3
	s_and_b32 s0, s0, -8
	s_sub_i32 s0, s69, s0
	s_cmp_lt_i32 s0, 0
	s_movk_i32 s5, 0x75
	s_cselect_b32 s5, s5, 0x74
	s_mul_i32 s0, s0, s5
	s_add_i32 s0, s0, s1
	s_mul_hi_i32 s1, s0, 0x8d3dcb09
	s_add_i32 s1, s1, s0
	s_lshr_b32 s5, s1, 31
	s_ashr_i32 s1, s1, 6
	s_add_i32 s1, s1, s5
	s_lshl_b32 s5, s1, 2
	s_mulk_i32 s1, 0x74
	s_sub_i32 s0, s0, s1
	s_bfe_i32 s1, s0, 0x80000
	s_bfe_u32 s1, s1, 0x2000d
	s_add_i32 s1, s0, s1
	s_bfe_i32 s6, s1, 0x80000
	s_and_b32 s1, s1, 0xfc
	s_sub_i32 s0, s0, s1
	s_sext_i32_i16 s6, s6
	s_sext_i32_i8 s0, s0
	s_add_i32 s0, s5, s0
	s_ashr_i32 s6, s6, 2

;     __device__ __forceinline__ size_t aoff(const Unit& u, const Gemm& g) const { return (size_t)u.pm * BM * g.K * g.esz; }
;     __device__ __forceinline__ size_t boff(const Unit& u, const Gemm& g) const { return (size_t)u.pn * BM * g.K * g.esz; }
;     __device__ bool next(int i, Unit& u) const { const int L = i * G + c; if (L >= 256) return false; u.g = L >> 6; const int r = L & 63; u.pm = r >> 1; u.pn = r & 1; return true; }
;     __device__ __forceinline__ size_t aoff(const Unit& u, const Gemm& g) const { return (size_t)(u.g * 32 + u.pm) * BM * g.K * g.esz; }
;     __device__ __forceinline__ size_t boff(const Unit& u, const Gemm& g) const { return (size_t)(u.g * 2 + u.pn) * BM * g.K * g.esz; }
;     __device__ bool next(int i, Unit& u) const {
;         const long L = (long)i * G + c; if (L >= nwg) return false;
;         int wgid = (int)L; { const int q = nwg / NXCD, r = nwg % NXCD, xcd = wgid % NXCD, off = wgid / NXCD; wgid = (xcd < r ? xcd * (q + 1) : r * (q + 1) + (xcd - r) * q) + off; }
;         const int nig = WGM * nN, gid = wgid / nig, fm = gid * WGM, gsz = (nM - fm) < WGM ? (nM - fm) : WGM;
;         u.pm = fm + ((wgid % nig) % gsz); u.pn = (wgid % nig) / gsz; u.g = 0; return true;
; template <class Epi, class Sched, bool I8 = false>
; __device__ __forceinline__ void gemm_phase(LAS unsigned char* lds, const Gemm g, const Sched& S, const Epi& E) {
;     ...
;         const bool has_next = S.next(ui + 1, nxt);
;         const char* nA = has_next ? (const char*)g.A + S.aoff(nxt, g) : cA; const char* nB = has_next ? (const char*)g.Bt + S.boff(nxt, g) : cB;
.LBB0_1479:
	s_add_i32 s66, s66, 1
	s_mul_i32 s4, s66, s60
	s_mul_hi_u32 s5, s66, s71
	s_add_i32 s5, s5, s4
	s_mul_i32 s4, s66, s71
	s_add_u32 s34, s4, s69
	s_addc_u32 s35, s5, s61
	v_cmp_gt_i64_e32 vcc, s[34:35], v[150:151]
	v_cmp_lt_i64_e64 s[4:5], s[34:35], v[148:149]
	s_cbranch_vccnz .LBB0_1481
	s_ashr_i32 s7, s34, 31
	s_lshr_b32 s7, s7, 29
	s_add_i32 s7, s34, s7
	s_ashr_i32 s28, s7, 3
	s_and_b32 s7, s7, -8
	s_sub_i32 s7, s34, s7
	s_cmp_lt_i32 s7, 0
	s_cselect_b32 s29, s62, 0x74
	s_mul_i32 s7, s7, s29
	s_add_i32 s7, s7, s28
	s_mul_hi_i32 s28, s7, 0x8d3dcb09
	s_add_i32 s28, s28, s7
	s_lshr_b32 s29, s28, 31
	s_ashr_i32 s28, s28, 6
	s_add_i32 s28, s28, s29
	s_lshl_b32 s29, s28, 2
	s_sub_i32 s30, 32, s29
	s_min_i32 s30, s30, 4
	s_abs_i32 s31, s30
	v_cvt_f32_u32_e32 v2, s31
	s_sub_i32 s35, 0, s31
	s_mulk_i32 s28, 0x74
	s_sub_i32 s7, s7, s28
	v_rcp_iflag_f32_e32 v2, v2
	s_abs_i32 s28, s7
	s_xor_b32 s34, s7, s30
	s_ashr_i32 s34, s34, 31
	v_mul_f32_e32 v2, 0x4f7ffffe, v2
	v_cvt_u32_f32_e32 v2, v2
	s_nop 0
	v_readfirstlane_b32 s36, v2
	s_mul_i32 s35, s35, s36
	s_mul_hi_u32 s35, s36, s35
	s_add_i32 s36, s36, s35
	s_mul_hi_u32 s35, s28, s36
	s_mul_i32 s36, s35, s31
	s_sub_i32 s28, s28, s36
	s_add_i32 s37, s35, 1
	s_sub_i32 s36, s28, s31
	s_cmp_ge_u32 s28, s31
	s_cselect_b32 s35, s37, s35
	s_cselect_b32 s28, s36, s28
	s_add_i32 s36, s35, 1
	s_cmp_ge_u32 s28, s31
	s_cselect_b32 s28, s36, s35
	s_xor_b32 s28, s28, s34
	s_sub_i32 s28, s28, s34
	s_mul_i32 s30, s28, s30
	s_sub_i32 s7, s7, s30
	s_add_i32 s30, s29, s7

; #define LAS __attribute__((address_space(3)))
; __device__ __forceinline__ void p0_convert(Frame& F, int lo, int hi, int worker, int nworkers) {
;     const int lane = (F.tid & 63), stride = nworkers * 8, first = lo + worker * 8 + F.wave;
;     LAS unsigned* T = (LAS unsigned*)(F.lds + F.wave * 16384);
;     if (first >= hi) return;
;     const int n_my = (hi - first + stride - 1) / stride;
;     f32x4 va[16], vb[16]; float ga, gb; P0Desc da, db;
;     p0_decode(F, first, da); p0_load(va, ga, da, lane);
;     for (int i = 0; i < n_my; i += 2) {
;         { const int j = i + 1 < n_my ? i + 1 : n_my - 1; p0_decode(F, first + j * stride, db); p0_load(vb, gb, db, lane); }
;         p0_finish(va, ga, da, T, lane);
;         { const int j = i + 2 < n_my ? i + 2 : n_my - 1; p0_decode(F, first + j * stride, da); p0_load(va, ga, da, lane); }
;         if (i + 1 < n_my) p0_finish(vb, gb, db, T, lane);
;     }
; }
; __device__ __forceinline__ void p0_convert_simple(Frame& F, int lo, int hi, int worker, int nworkers) {
;     const int lane = (F.tid & 63), stride = nworkers * 8;
;     LAS unsigned* T = (LAS unsigned*)(F.lds + F.wave * 16384);
;     for (int it = lo + worker * 8 + F.wave; it < hi; it += stride) { f32x4 va[16]; float ga; P0Desc da; p0_decode(F, it, da); p0_load(va, ga, da, lane); p0_finish(va, ga, da, T, lane); }
; }
; __device__ __forceinline__ void tail_convert(Frame& F, int nwg, int lo, int hi) {
;     const int r = nwg % F.G, c = (int)blockIdx.x;
;     if (r == 0) p0_convert(F, lo, hi, c, F.G);
;     else if (c >= r) p0_convert_simple(F, lo, hi, c - r, F.G - r);
; }
.LBB0_1681:
	s_abs_i32 s0, s71
	s_waitcnt vmcnt(1)
	v_cvt_f32_u32_e32 v2, s0
	s_sub_i32 s1, 0, s0
	v_rcp_iflag_f32_e32 v2, v2
	s_nop 0
	v_mul_f32_e32 v2, 0x4f7ffffe, v2
	v_cvt_u32_f32_e32 v2, v2
	s_nop 0
	v_readfirstlane_b32 s2, v2
	s_mul_i32 s1, s1, s2
	s_mul_hi_u32 s1, s2, s1
	s_add_i32 s2, s2, s1
	s_mul_hi_u32 s1, s2, 0x3a0
	s_mul_i32 s1, s1, s0
	s_sub_i32 s1, 0x3a0, s1
	s_sub_i32 s2, s1, s0
	s_cmp_ge_u32 s1, s0
	s_cselect_b32 s1, s2, s1
	s_sub_i32 s2, s1, s0
	s_cmp_ge_u32 s1, s0
	s_cselect_b32 s30, s2, s1
	s_cmp_lg_u32 s30, 0
	s_cselect_b64 s[6:7], -1, 0
	s_and_b64 vcc, exec, s[6:7]
	s_cbranch_vccz .LBB0_1825
	s_cmp_lt_i32 s69, s30
	s_cbranch_scc1 .LBB0_1824
	s_sub_i32 s0, s69, s30
	s_lshl_b32 s0, s0, 3
	s_add_i32 s0, s68, s0
	s_add_i32 s0, s0, 0x11e40
	s_cmp_gt_u32 s0, 0x12e3f
	s_cbranch_scc1 .LBB0_1824
	s_sub_i32 s1, s71, s30
	s_lshl_b32 s14, s1, 3
	s_lshl_b32 s1, s68, 14
	s_add_i32 s1, s1, 0
	v_bfe_u32 v2, v0, 4, 2
	s_waitcnt lgkmcnt(0)
	v_and_b32_e32 v5, 7, v0
	s_add_u32 s8, s78, 0x13e00000
	v_lshl_add_u32 v3, v2, 2, s1
	v_lshl_add_u32 v6, v5, 4, s1
	s_addc_u32 s9, s79, 0
	s_lshl_b32 s1, s69, 3
	v_mbcnt_lo_u32_b32 v7, -1, 0
	v_lshlrev_b32_e32 v72, 1, v2
	s_add_i32 s1, s68, s1
	s_lshl_b32 s2, s30, 3
	v_mbcnt_hi_u32_b32 v7, -1, v7
	v_and_b32_e32 v69, 60, v141
	v_bfe_u32 v70, v0, 3, 3
	v_or_b32_e32 v2, 1, v72
	s_sub_i32 s1, s1, s2
	v_and_b32_e32 v95, 64, v7
	v_mul_u32_u24_e32 v4, 0x84, v69
	v_lshlrev_b32_e32 v87, 3, v5
	v_mul_u32_u24_e32 v5, 0x84, v70
	s_add_i32 s15, s1, 0x1493f
	s_lshl_b32 s16, s0, 6
	s_lshl_b32 s0, s71, 9
	s_lshl_b32 s1, s30, 9
	v_or_b32_e32 v2, v95, v2
	v_and_b32_e32 v68, 63, v0
	s_mov_b32 s5, 0
	v_and_b32_e32 v71, 6, v70
	v_or_b32_e32 v73, 8, v72
	v_or_b32_e32 v74, 9, v72
	v_or_b32_e32 v75, 16, v72
	v_or_b32_e32 v76, 17, v72
	v_or_b32_e32 v77, 24, v72
	v_or_b32_e32 v78, 25, v72
	v_or_b32_e32 v79, 32, v72
	v_or_b32_e32 v80, 33, v72
	v_or_b32_e32 v81, 40, v72
	v_or_b32_e32 v82, 41, v72
	v_or_b32_e32 v83, 48, v72
	v_or_b32_e32 v84, 49, v72
	v_or_b32_e32 v85, 56, v72
	v_or_b32_e32 v86, 57, v72
	v_or_b32_e32 v88, 8, v70
	v_or_b32_e32 v89, 16, v70
	v_or_b32_e32 v90, 24, v70
	v_or_b32_e32 v91, 32, v70
	v_or_b32_e32 v92, 40, v70
	v_or_b32_e32 v93, 48, v70
	v_or_b32_e32 v94, 56, v70
	s_sub_i32 s17, s0, s1
	s_add_i32 s18, 0, 0x27c78
	s_add_i32 s19, 0, 0x27c28
	s_add_i32 s20, 0, 0x27c30
	s_mov_b32 s21, 0xae00000
	s_mov_b32 s22, 0x27c20
	s_add_i32 s23, 0, 0x27c10
	s_add_i32 s24, 0, 0x27c18
	s_mov_b32 s25, 0x27c90
	s_mov_b32 s26, 0x200000
	s_mov_b32 s27, 0x27c08
	s_movk_i32 s28, 0x13ff
	s_movk_i32 s29, 0x142f
	v_mov_b32_e32 v67, 0
	v_lshlrev_b32_e32 v96, 2, v2
	v_add_u32_e32 v97, v3, v4
	v_add_u32_e32 v98, v6, v5
	s_branch .LBB0_1686

; __device__ __forceinline__ void qkt(f32x16& p0, f32x16& p1, const LAS unsigned char* Kt, int r32, int hi, const bf16x8* qr, float init) {
;     f32x16 zi;
; #pragma unroll
;     for (int r = 0; r < 16; ++r) zi[r] = init;
;     const int kt = (int)(uintptr_t)Kt;
;     const int a0 = kt + KSWZ(r32, (0 * 16 + hi * 8) * 2), a1 = kt + KSWZ(r32, (1 * 16 + hi * 8) * 2), a2 = kt + KSWZ(r32, (2 * 16 + hi * 8) * 2), a3 = kt + KSWZ(r32, (3 * 16 + hi * 8) * 2);
;     ...
;     bf16x8 f0, f1, f2, f3, g0, g1, g2, g3, f4, f5, f6, f7, g4, g5, g6, g7;
;     DSR128(f0, a0, 0); DSR128(g0, a0, 8192); DSR128(f1, a1, 0); DSR128(g1, a1, 8192); DSR128(f2, a2, 0); DSR128(g2, a2, 8192); DSR128(f3, a3, 0); DSR128(g3, a3, 8192);
;     asm volatile("s_waitcnt lgkmcnt(0)" : "+v"(f0), "+v"(g0), "+v"(f1), "+v"(g1), "+v"(f2), "+v"(g2), "+v"(f3), "+v"(g3) :: "memory");
;     DSR128(f4, a0, 128); DSR128(g4, a0, 8320); DSR128(f5, a1, 128); DSR128(g5, a1, 8320); DSR128(f6, a2, 128); DSR128(g6, a2, 8320); DSR128(f7, a3, 128); DSR128(g7, a3, 8320);
;     SBAR();
;     p0 = __builtin_amdgcn_mfma_f32_32x32x16_bf16(f0, qr[0], zi, 0, 0, 0); p1 = __builtin_amdgcn_mfma_f32_32x32x16_bf16(g0, qr[0], zi, 0, 0, 0);
;     p0 = __builtin_amdgcn_mfma_f32_32x32x16_bf16(f1, qr[1], p0, 0, 0, 0); p1 = __builtin_amdgcn_mfma_f32_32x32x16_bf16(g1, qr[1], p1, 0, 0, 0);
;     p0 = __builtin_amdgcn_mfma_f32_32x32x16_bf16(f2, qr[2], p0, 0, 0, 0); p1 = __builtin_amdgcn_mfma_f32_32x32x16_bf16(g2, qr[2], p1, 0, 0, 0);
;     p0 = __builtin_amdgcn_mfma_f32_32x32x16_bf16(f3, qr[3], p0, 0, 0, 0); p1 = __builtin_amdgcn_mfma_f32_32x32x16_bf16(g3, qr[3], p1, 0, 0, 0);
;     asm volatile("s_waitcnt lgkmcnt(0)" : "+v"(f4), "+v"(g4), "+v"(f5), "+v"(g5), "+v"(f6), "+v"(g6), "+v"(f7), "+v"(g7) :: "memory");
;     SBAR();
;     p0 = __builtin_amdgcn_mfma_f32_32x32x16_bf16(f4, qr[4], p0, 0, 0, 0); p1 = __builtin_amdgcn_mfma_f32_32x32x16_bf16(g4, qr[4], p1, 0, 0, 0);
;     p0 = __builtin_amdgcn_mfma_f32_32x32x16_bf16(f5, qr[5], p0, 0, 0, 0); p1 = __builtin_amdgcn_mfma_f32_32x32x16_bf16(g5, qr[5], p1, 0, 0, 0);
;     p0 = __builtin_amdgcn_mfma_f32_32x32x16_bf16(f6, qr[6], p0, 0, 0, 0); p1 = __builtin_amdgcn_mfma_f32_32x32x16_bf16(g6, qr[6], p1, 0, 0, 0);
;     p0 = __builtin_amdgcn_mfma_f32_32x32x16_bf16(f7, qr[7], p0, 0, 0, 0); p1 = __builtin_amdgcn_mfma_f32_32x32x16_bf16(g7, qr[7], p1, 0, 0, 0);
;     ...
; }
.LBB0_3058:
	s_and_b32 s0, s7, 0x4000
	s_add_i32 s12, s9, 32
	s_cmp_gt_i32 s12, s8
	s_cbranch_scc1 .Lmy_ldskip_0
	v_subrev_u32_e32 v94, 32, v158
	v_ashrrev_i32_e32 v95, 31, v94
	v_lshlrev_b64 v[94:95], 8, v[94:95]
	v_mov_b32_e32 v96, v158
	v_ashrrev_i32_e32 v97, 31, v158
	v_lshl_add_u64 v[88:89], v[154:155], 0, v[94:95]
	v_lshlrev_b64 v[90:91], 8, v[96:97]
	v_lshl_add_u64 v[94:95], v[156:157], 0, v[94:95]
	v_lshl_add_u64 v[92:93], v[154:155], 0, v[90:91]
	global_load_dwordx4 v[132:135], v[88:89], off
	global_load_dwordx4 v[136:139], v[92:93], off
	v_lshl_add_u64 v[88:89], v[156:157], 0, v[90:91]
	global_load_dwordx4 v[140:143], v[94:95], off
	global_load_dwordx4 v[144:147], v[88:89], off
.Lmy_ldskip_0:
	s_add_i32 s11, s0, 0
	s_add_i32 s0, s11, 0xc000
	v_bfe_u32 v2, v160, s12, 1
	v_cmp_eq_u32_e32 vcc, 0, v2
	v_add_u32_e32 v2, s0, v172
	ds_read_b128 v[182:185], v2 offset:0
	ds_read_b128 v[186:189], v2 offset:0x2000
	v_add_u32_e32 v84, s0, v173
	ds_read_b128 v[190:193], v84 offset:0
	ds_read_b128 v[194:197], v84 offset:0x2000
	v_add_u32_e32 v85, s0, v174
	ds_read_b128 v[198:201], v85 offset:0
	ds_read_b128 v[202:205], v85 offset:0x2000
	v_add_u32_e32 v86, s0, v175
	ds_read_b128 v[206:209], v86 offset:0
	ds_read_b128 v[210:213], v86 offset:0x2000
	v_cndmask_b32_e32 v68, 0, v163, vcc
	s_waitcnt lgkmcnt(0)
	ds_read_b128 v[214:217], v2 offset:0x80
	ds_read_b128 v[218:221], v2 offset:0x2080
	ds_read_b128 v[222:225], v84 offset:0x80
	ds_read_b128 v[226:229], v84 offset:0x2080
	ds_read_b128 v[230:233], v85 offset:0x80
	ds_read_b128 v[234:237], v85 offset:0x2080
	ds_read_b128 v[238:241], v86 offset:0x80
	ds_read_b128 v[242:245], v86 offset:0x2080
	v_mov_b32_e32 v69, v68
	v_mov_b32_e32 v70, v68
	v_mov_b32_e32 v71, v68
	v_mov_b32_e32 v72, v68
	v_mov_b32_e32 v73, v68
	v_mov_b32_e32 v74, v68
	v_mov_b32_e32 v75, v68
	v_mov_b32_e32 v76, v68
	v_mov_b32_e32 v77, v68
	v_mov_b32_e32 v78, v68
	v_mov_b32_e32 v79, v68
	v_mov_b32_e32 v80, v68
	v_mov_b32_e32 v81, v68
	v_mov_b32_e32 v82, v68
	v_mov_b32_e32 v83, v68
	s_nop 1
	v_mfma_f32_32x32x16_bf16 v[84:99], v[182:185], v[100:103], v[68:83]
	v_mfma_f32_32x32x16_bf16 v[68:83], v[186:189], v[100:103], v[68:83]
	v_mfma_f32_32x32x16_bf16 v[84:99], v[190:193], v[104:107], v[84:99]
	v_mfma_f32_32x32x16_bf16 v[68:83], v[194:197], v[104:107], v[68:83]
	v_mfma_f32_32x32x16_bf16 v[84:99], v[198:201], v[108:111], v[84:99]
	v_mfma_f32_32x32x16_bf16 v[68:83], v[202:205], v[108:111], v[68:83]
	v_mfma_f32_32x32x16_bf16 v[84:99], v[206:209], v[112:115], v[84:99]
	v_mfma_f32_32x32x16_bf16 v[68:83], v[210:213], v[112:115], v[68:83]
	s_waitcnt lgkmcnt(0)
	v_mfma_f32_32x32x16_bf16 v[84:99], v[214:217], v[116:119], v[84:99]
	s_cmp_ge_i32 s76, s95
	v_mfma_f32_32x32x16_bf16 v[68:83], v[218:221], v[116:119], v[68:83]
	v_mfma_f32_32x32x16_bf16 v[84:99], v[222:225], v[120:123], v[84:99]
	v_mfma_f32_32x32x16_bf16 v[68:83], v[226:229], v[120:123], v[68:83]
	v_mfma_f32_32x32x16_bf16 v[84:99], v[230:233], v[124:127], v[84:99]
	v_mfma_f32_32x32x16_bf16 v[68:83], v[234:237], v[124:127], v[68:83]
	v_mfma_f32_32x32x16_bf16 v[84:99], v[238:241], v[128:131], v[84:99]
	v_mfma_f32_32x32x16_bf16 v[68:83], v[242:245], v[128:131], v[68:83]
	s_cbranch_scc1 .LBB0_3060
	ds_read_b32 v182, v179 offset:0xec
	ds_read_b32 v184, v179 offset:0x6c
	ds_read_b32 v183, v179 offset:0xe8
	ds_read_b32 v185, v179 offset:0x68
	ds_read_b32 v186, v179 offset:0xe4
	ds_read_b32 v188, v179 offset:0x64
	ds_read_b32 v187, v179 offset:0xe0
	ds_read_b32 v189, v179 offset:0x60
	ds_read_b32 v190, v179 offset:0xcc
	ds_read_b32 v192, v179 offset:0x4c
	ds_read_b32 v191, v179 offset:0xc8
	ds_read_b32 v193, v179 offset:0x48
	ds_read_b32 v194, v179 offset:0xc4
	ds_read_b32 v196, v179 offset:0x44
	ds_read_b32 v195, v179 offset:0xc0
	ds_read_b32 v197, v179 offset:64
	ds_read_b32 v198, v179 offset:0xac
	ds_read_b32 v200, v179 offset:44
	ds_read_b32 v199, v179 offset:0xa8
	ds_read_b32 v201, v179 offset:40
	ds_read_b32 v202, v179 offset:0xa4
	ds_read_b32 v204, v179 offset:36
	ds_read_b32 v203, v179 offset:0xa0
	ds_read_b32 v205, v179 offset:32
	ds_read_b32 v206, v179 offset:0x8c
	ds_read_b32 v208, v179 offset:12
	ds_read_b32 v207, v179 offset:0x88
	ds_read_b32 v209, v179 offset:8
	ds_read_b32 v210, v179 offset:0x84
	ds_read_b32 v212, v179 offset:4
	ds_read_b32 v211, v179 offset:0x80
	ds_read_b32 v213, v179 offset:0
	s_nop 0
	s_waitcnt lgkmcnt(0)
	s_nop 8
	v_pk_add_f32 v[98:99], v[98:99], v[210:211]
	v_pk_add_f32 v[96:97], v[96:97], v[206:207]
	v_pk_add_f32 v[94:95], v[94:95], v[202:203]
	v_pk_add_f32 v[92:93], v[92:93], v[198:199]
	v_pk_add_f32 v[90:91], v[90:91], v[194:195]
	v_pk_add_f32 v[88:89], v[88:89], v[190:191]
	v_pk_add_f32 v[86:87], v[86:87], v[186:187]
	v_pk_add_f32 v[84:85], v[84:85], v[182:183]
	v_pk_add_f32 v[82:83], v[82:83], v[212:213]
	v_pk_add_f32 v[80:81], v[80:81], v[208:209]
	v_pk_add_f32 v[78:79], v[78:79], v[204:205]
	v_pk_add_f32 v[76:77], v[76:77], v[200:201]
	v_pk_add_f32 v[74:75], v[74:75], v[196:197]
	v_pk_add_f32 v[72:73], v[72:73], v[192:193]
	v_pk_add_f32 v[70:71], v[70:71], v[188:189]
	v_pk_add_f32 v[68:69], v[68:69], v[184:185]

; #define LAS __attribute__((address_space(3)))
; #define SBAR() __builtin_amdgcn_sched_barrier(0)
; __device__ __forceinline__ int v_st(int k, int c) { const int kk = (k & ~0xC) | ((k & 4) << 1) | ((k & 8) >> 1); return ((kk >> 3) * 4 + (c >> 5)) * 512 + ((kk & 7) * 32 + (c & 31)) * 2; }
; __device__ __forceinline__ void pv_tile(f32x16* o, int vb, bf16x8 pa0, bf16x8 pa1, bf16x8 pa2, bf16x8 pa3) {
;     ...
;     PV_D0(0); PV_D0(1); PV_D0(2); PV_D0(3);
;     ...
; }
; __device__ __forceinline__ void pack_p(const f32x16& p0, const f32x16& p1, bf16x8& pa0, bf16x8& pa1, bf16x8& pa2, bf16x8& pa3) {
;     ...
;     PK4(p0, 0, pa0); PK4(p0, 8, pa1); PK4(p1, 0, pa2); PK4(p1, 8, pa3);
;     ...
; }
; __device__ __forceinline__ float half_swap_max(float v) { auto rr = __builtin_amdgcn_permlane32_swap(__float_as_uint(v), __float_as_uint(v), false, false); return fmaxf(__uint_as_float(rr[0]), __uint_as_float(rr[1])); }
; __device__ __forceinline__ float half_swap_sum(float v) { auto rr = __builtin_amdgcn_permlane32_swap(__float_as_uint(v), __float_as_uint(v), false, false); return __uint_as_float(rr[0]) + __uint_as_float(rr[1]); }
; __device__ __forceinline__ void tile_write(const TileStage& T, LAS unsigned char* lds, int kbuf, int vbuf, int sr, int sc) {
;     const int kws = KSWZ(sr, sc * 2);
;     *(LAS bf16x8*)(lds + AT_K + kbuf * SHM_T + kws) = T.k0; *(LAS bf16x8*)(lds + AT_K + kbuf * SHM_T + kws + 32 * 256) = T.k1;
;     *(LAS bf16x8*)(lds + AT_V + vbuf * SHM_T + v_st(sr, sc)) = T.v0; *(LAS bf16x8*)(lds + AT_V + vbuf * SHM_T + v_st(32 + sr, sc)) = T.v1;
; }
; template <int MODE>
; __device__ __forceinline__ void attn_branch(Frame& F, const bf16_t* Kp, const bf16_t* Vp, int j_lo, int j_hi, int sb, const bf16x8* qr, unsigned smask, f32x16* o, float& l_out) {
;     ...
;         float ps = 0.f;
; #pragma unroll
;         for (int r = 0; r < 16; ++r) { C0[r] = __builtin_amdgcn_exp2f(C0[r] - m_reg); C1[r] = __builtin_amdgcn_exp2f(C1[r] - m_reg); ps += C0[r] + C1[r]; }
;         ps = half_swap_sum(ps);
;         l_reg = l_reg * alpha + ps;
;         bf16x8 pa0, pa1, pa2, pa3; pack_p(C0, C1, pa0, pa1, pa2, pa3);
;         if (t + 2 < NT) tile_load(T, Kp, Vp, (j + 2) * 64, sr, sc);
;         SBAR();
;         pv_tile(o, vb0 + vs * SHM_T, pa0, pa1, pa2, pa3);
;         if (t + 2 < NT) tile_write(T, lds, t & 1, vs == 0 ? 2 : vs - 1, sr, sc);
.LBB0_3067:
	v_sub_f32_e32 v84, v84, v2
	v_sub_f32_e32 v68, v68, v2
	v_exp_f32_e32 v159, v84
	v_exp_f32_e32 v183, v68
	v_sub_f32_e32 v68, v85, v2
	v_sub_f32_e32 v69, v69, v2
	v_exp_f32_e32 v68, v68
	v_exp_f32_e32 v184, v69
	v_add_f32_e32 v69, v159, v183
	v_sub_f32_e32 v85, v86, v2
	v_sub_f32_e32 v70, v70, v2
	v_add_f32_e32 v69, 0, v69
	v_add_f32_e32 v84, v68, v184
	v_exp_f32_e32 v86, v85
	v_exp_f32_e32 v185, v70
	v_sub_f32_e32 v70, v87, v2
	v_sub_f32_e32 v71, v71, v2
	v_exp_f32_e32 v70, v70
	v_exp_f32_e32 v87, v71
	v_add_f32_e32 v69, v84, v69
	v_sub_f32_e32 v84, v88, v2
	v_sub_f32_e32 v72, v72, v2
	v_exp_f32_e32 v88, v84
	v_exp_f32_e32 v186, v72
	v_sub_f32_e32 v72, v89, v2
	v_sub_f32_e32 v73, v73, v2
	v_exp_f32_e32 v72, v72
	v_exp_f32_e32 v89, v73
	v_sub_f32_e32 v73, v90, v2
	v_sub_f32_e32 v74, v74, v2
	v_add_f32_e32 v71, v86, v185
	v_exp_f32_e32 v73, v73
	v_exp_f32_e32 v90, v74
	v_sub_f32_e32 v74, v91, v2
	v_sub_f32_e32 v75, v75, v2
	v_add_f32_e32 v69, v71, v69
	v_add_f32_e32 v71, v70, v87
	v_exp_f32_e32 v74, v74
	v_exp_f32_e32 v91, v75
	v_sub_f32_e32 v75, v92, v2
	v_sub_f32_e32 v76, v76, v2
	v_add_f32_e32 v69, v71, v69
	v_add_f32_e32 v71, v88, v186
	v_exp_f32_e32 v75, v75
	v_exp_f32_e32 v76, v76
	v_sub_f32_e32 v84, v93, v2
	v_sub_f32_e32 v77, v77, v2
	v_add_f32_e32 v69, v71, v69
	v_add_f32_e32 v71, v72, v89
	v_exp_f32_e32 v92, v84
	v_exp_f32_e32 v77, v77
	v_sub_f32_e32 v84, v94, v2
	v_sub_f32_e32 v78, v78, v2
	v_add_f32_e32 v69, v71, v69
	v_add_f32_e32 v71, v73, v90
	v_exp_f32_e32 v93, v84
	v_exp_f32_e32 v78, v78
	v_sub_f32_e32 v84, v95, v2
	v_sub_f32_e32 v79, v79, v2
	v_add_f32_e32 v69, v71, v69
	v_add_f32_e32 v71, v74, v91
	v_exp_f32_e32 v94, v84
	v_exp_f32_e32 v79, v79
	v_sub_f32_e32 v84, v96, v2
	v_sub_f32_e32 v80, v80, v2
	v_add_f32_e32 v69, v71, v69
	v_add_f32_e32 v71, v75, v76
	v_exp_f32_e32 v95, v84
	v_exp_f32_e32 v96, v80
	v_sub_f32_e32 v80, v97, v2
	v_sub_f32_e32 v81, v81, v2
	v_add_f32_e32 v69, v71, v69
	v_add_f32_e32 v71, v92, v77
	v_exp_f32_e32 v80, v80
	v_exp_f32_e32 v97, v81
	v_sub_f32_e32 v81, v98, v2
	v_sub_f32_e32 v82, v82, v2
	v_add_f32_e32 v69, v71, v69
	v_add_f32_e32 v71, v93, v78
	v_exp_f32_e32 v81, v81
	v_exp_f32_e32 v98, v82
	v_sub_f32_e32 v82, v99, v2
	v_sub_f32_e32 v83, v83, v2
	v_add_f32_e32 v69, v71, v69
	v_add_f32_e32 v71, v94, v79
	v_exp_f32_e32 v82, v82
	v_exp_f32_e32 v99, v83
	v_add_f32_e32 v69, v71, v69
	v_add_f32_e32 v71, v95, v96
	v_add_f32_e32 v69, v71, v69
	v_add_f32_e32 v71, v80, v97
	v_add_f32_e32 v69, v71, v69
	v_add_f32_e32 v71, v81, v98
	v_add_f32_e32 v69, v71, v69
	v_add_f32_e32 v71, v82, v99
	v_add_f32_e32 v84, v71, v69
	v_mov_b32_e32 v85, v84
	v_cvt_pk_bf16_f32 v68, v159, v68
	v_cvt_pk_bf16_f32 v69, v86, v70
	v_cvt_pk_bf16_f32 v70, v88, v72
	v_cvt_pk_bf16_f32 v71, v73, v74
	v_cvt_pk_bf16_f32 v72, v75, v92
	v_cvt_pk_bf16_f32 v73, v93, v94
	v_cvt_pk_bf16_f32 v74, v95, v80
	v_cvt_pk_bf16_f32 v75, v81, v82
	v_cvt_pk_bf16_f32 v80, v183, v184
	v_cvt_pk_bf16_f32 v81, v185, v87
	v_cvt_pk_bf16_f32 v82, v186, v89
	v_cvt_pk_bf16_f32 v83, v90, v91
	v_cvt_pk_bf16_f32 v76, v76, v77
	v_cvt_pk_bf16_f32 v77, v78, v79
	v_cvt_pk_bf16_f32 v78, v96, v97
	v_cvt_pk_bf16_f32 v79, v98, v99
	s_cmp_le_i32 s12, s8
	s_nop 0
	v_permlane32_swap_b32_e32 v84, v85
	v_permlane32_swap_b32_e32 v68, v70
	v_permlane32_swap_b32_e32 v69, v71
	v_permlane32_swap_b32_e32 v72, v74
	v_permlane32_swap_b32_e32 v73, v75
	v_permlane32_swap_b32_e32 v80, v82
	v_permlane32_swap_b32_e32 v81, v83
	v_permlane32_swap_b32_e32 v76, v78
	s_cselect_b64 s[0:1], -1, 0
	s_cmp_gt_i32 s12, s8
	v_permlane32_swap_b32_e32 v77, v79
	s_cbranch_scc1 .LBB0_3069
.LBB0_3069:
	s_lshl_b32 s12, s10, 14
	v_add_u32_e32 v98, s12, v178
	ds_read_b64_tr_b16 v[86:87], v98 offset:0
	ds_read_b64_tr_b16 v[88:89], v98 offset:0x800
	ds_read_b64_tr_b16 v[90:91], v98 offset:0x1000
	ds_read_b64_tr_b16 v[92:93], v98 offset:0x1800
	ds_read_b64_tr_b16 v[94:95], v98 offset:0x2000
	ds_read_b64_tr_b16 v[96:97], v98 offset:0x2800
	ds_read_b64_tr_b16 v[184:185], v98 offset:0x3000
	ds_read_b64_tr_b16 v[186:187], v98 offset:0x3800
	s_waitcnt lgkmcnt(0)
	s_nop 0
	v_mfma_f32_32x32x16_bf16 v[52:67], v[68:71], v[86:89], v[52:67]
	ds_read_b64_tr_b16 v[86:87], v98 offset:0x200
	ds_read_b64_tr_b16 v[88:89], v98 offset:0xa00
	v_mfma_f32_32x32x16_bf16 v[52:67], v[72:75], v[90:93], v[52:67]
	ds_read_b64_tr_b16 v[90:91], v98 offset:0x1200
	ds_read_b64_tr_b16 v[92:93], v98 offset:0x1a00
	v_mfma_f32_32x32x16_bf16 v[52:67], v[80:83], v[94:97], v[52:67]
	ds_read_b64_tr_b16 v[94:95], v98 offset:0x2200
	ds_read_b64_tr_b16 v[96:97], v98 offset:0x2a00
	v_mfma_f32_32x32x16_bf16 v[52:67], v[76:79], v[184:187], v[52:67]
	ds_read_b64_tr_b16 v[184:185], v98 offset:0x3200
	ds_read_b64_tr_b16 v[186:187], v98 offset:0x3a00
	s_waitcnt lgkmcnt(0)
	v_mfma_f32_32x32x16_bf16 v[36:51], v[68:71], v[86:89], v[36:51]
	ds_read_b64_tr_b16 v[86:87], v98 offset:0x400
	ds_read_b64_tr_b16 v[88:89], v98 offset:0xc00
	v_mfma_f32_32x32x16_bf16 v[36:51], v[72:75], v[90:93], v[36:51]
	ds_read_b64_tr_b16 v[90:91], v98 offset:0x1400
	ds_read_b64_tr_b16 v[92:93], v98 offset:0x1c00
	v_mfma_f32_32x32x16_bf16 v[36:51], v[80:83], v[94:97], v[36:51]
	ds_read_b64_tr_b16 v[94:95], v98 offset:0x2400
	ds_read_b64_tr_b16 v[96:97], v98 offset:0x2c00
	v_mfma_f32_32x32x16_bf16 v[36:51], v[76:79], v[184:187], v[36:51]
	ds_read_b64_tr_b16 v[184:185], v98 offset:0x3400
	ds_read_b64_tr_b16 v[186:187], v98 offset:0x3c00
	s_waitcnt lgkmcnt(0)
	v_mfma_f32_32x32x16_bf16 v[20:35], v[68:71], v[86:89], v[20:35]
	ds_read_b64_tr_b16 v[86:87], v98 offset:0x600
	ds_read_b64_tr_b16 v[88:89], v98 offset:0xe00
	v_mfma_f32_32x32x16_bf16 v[20:35], v[72:75], v[90:93], v[20:35]
	ds_read_b64_tr_b16 v[90:91], v98 offset:0x1600
	ds_read_b64_tr_b16 v[92:93], v98 offset:0x1e00
	v_mfma_f32_32x32x16_bf16 v[20:35], v[80:83], v[94:97], v[20:35]
	ds_read_b64_tr_b16 v[94:95], v98 offset:0x2600
	ds_read_b64_tr_b16 v[96:97], v98 offset:0x2e00
	v_mfma_f32_32x32x16_bf16 v[20:35], v[76:79], v[184:187], v[20:35]
	ds_read_b64_tr_b16 v[184:185], v98 offset:0x3600
	ds_read_b64_tr_b16 v[186:187], v98 offset:0x3e00
	s_waitcnt lgkmcnt(0)
	v_mfma_f32_32x32x16_bf16 v[4:19], v[68:71], v[86:89], v[4:19]
	s_andn2_b64 vcc, exec, s[0:1]
	v_mfma_f32_32x32x16_bf16 v[4:19], v[72:75], v[90:93], v[4:19]
	v_mfma_f32_32x32x16_bf16 v[4:19], v[80:83], v[94:97], v[4:19]
	v_mfma_f32_32x32x16_bf16 v[4:19], v[76:79], v[184:187], v[4:19]
	s_cbranch_vccnz .LBB0_3071
	s_addk_i32 s12, 0xc000
	s_cmp_lg_u32 s10, 0
	s_cselect_b32 s0, s12, 0x8000
	v_add_u32_e32 v68, s0, v169
	v_add3_u32 v70, s11, v161, v167
	v_add3_u32 v69, v68, v171, v168
	v_add3_u32 v68, v68, v170, v168
	s_waitcnt vmcnt(3)
	ds_write_b128 v70, v[132:135] offset:49152
	s_waitcnt vmcnt(2)
	ds_write_b128 v70, v[136:139] offset:57344
	s_waitcnt vmcnt(1)
	ds_write_b128 v68, v[140:143]
	s_waitcnt vmcnt(0)
	ds_write_b128 v69, v[144:147]

; __device__ __forceinline__ void qkt(f32x16& p0, f32x16& p1, const LAS unsigned char* Kt, int r32, int hi, const bf16x8* qr, float init) {
;     f32x16 zi;
; #pragma unroll
;     for (int r = 0; r < 16; ++r) zi[r] = init;
;     const int kt = (int)(uintptr_t)Kt;
;     const int a0 = kt + KSWZ(r32, (0 * 16 + hi * 8) * 2), a1 = kt + KSWZ(r32, (1 * 16 + hi * 8) * 2), a2 = kt + KSWZ(r32, (2 * 16 + hi * 8) * 2), a3 = kt + KSWZ(r32, (3 * 16 + hi * 8) * 2);
;     ...
;     bf16x8 f0, f1, f2, f3, g0, g1, g2, g3, f4, f5, f6, f7, g4, g5, g6, g7;
;     DSR128(f0, a0, 0); DSR128(g0, a0, 8192); DSR128(f1, a1, 0); DSR128(g1, a1, 8192); DSR128(f2, a2, 0); DSR128(g2, a2, 8192); DSR128(f3, a3, 0); DSR128(g3, a3, 8192);
;     asm volatile("s_waitcnt lgkmcnt(0)" : "+v"(f0), "+v"(g0), "+v"(f1), "+v"(g1), "+v"(f2), "+v"(g2), "+v"(f3), "+v"(g3) :: "memory");
;     DSR128(f4, a0, 128); DSR128(g4, a0, 8320); DSR128(f5, a1, 128); DSR128(g5, a1, 8320); DSR128(f6, a2, 128); DSR128(g6, a2, 8320); DSR128(f7, a3, 128); DSR128(g7, a3, 8320);
;     SBAR();
;     p0 = __builtin_amdgcn_mfma_f32_32x32x16_bf16(f0, qr[0], zi, 0, 0, 0); p1 = __builtin_amdgcn_mfma_f32_32x32x16_bf16(g0, qr[0], zi, 0, 0, 0);
;     p0 = __builtin_amdgcn_mfma_f32_32x32x16_bf16(f1, qr[1], p0, 0, 0, 0); p1 = __builtin_amdgcn_mfma_f32_32x32x16_bf16(g1, qr[1], p1, 0, 0, 0);
;     p0 = __builtin_amdgcn_mfma_f32_32x32x16_bf16(f2, qr[2], p0, 0, 0, 0); p1 = __builtin_amdgcn_mfma_f32_32x32x16_bf16(g2, qr[2], p1, 0, 0, 0);
;     p0 = __builtin_amdgcn_mfma_f32_32x32x16_bf16(f3, qr[3], p0, 0, 0, 0); p1 = __builtin_amdgcn_mfma_f32_32x32x16_bf16(g3, qr[3], p1, 0, 0, 0);
;     asm volatile("s_waitcnt lgkmcnt(0)" : "+v"(f4), "+v"(g4), "+v"(f5), "+v"(g5), "+v"(f6), "+v"(g6), "+v"(f7), "+v"(g7) :: "memory");
;     SBAR();
;     p0 = __builtin_amdgcn_mfma_f32_32x32x16_bf16(f4, qr[4], p0, 0, 0, 0); p1 = __builtin_amdgcn_mfma_f32_32x32x16_bf16(g4, qr[4], p1, 0, 0, 0);
;     p0 = __builtin_amdgcn_mfma_f32_32x32x16_bf16(f5, qr[5], p0, 0, 0, 0); p1 = __builtin_amdgcn_mfma_f32_32x32x16_bf16(g5, qr[5], p1, 0, 0, 0);
;     p0 = __builtin_amdgcn_mfma_f32_32x32x16_bf16(f6, qr[6], p0, 0, 0, 0); p1 = __builtin_amdgcn_mfma_f32_32x32x16_bf16(g6, qr[6], p1, 0, 0, 0);
;     p0 = __builtin_amdgcn_mfma_f32_32x32x16_bf16(f7, qr[7], p0, 0, 0, 0); p1 = __builtin_amdgcn_mfma_f32_32x32x16_bf16(g7, qr[7], p1, 0, 0, 0);
;     ...
; }
.LBB0_3081:
	s_and_b32 s0, s11, 0x4000
	s_cmp_gt_i32 s7, s6
	s_cbranch_scc1 .Lmy_ldskip_1
	v_mov_b32_e32 v96, v158
	v_ashrrev_i32_e32 v97, 31, v158
	v_add_u32_e32 v90, 32, v158
	v_lshlrev_b64 v[94:95], 8, v[96:97]
	v_ashrrev_i32_e32 v91, 31, v90
	v_lshl_add_u64 v[88:89], v[154:155], 0, v[94:95]
	v_lshlrev_b64 v[90:91], 8, v[90:91]
	v_lshl_add_u64 v[94:95], v[156:157], 0, v[94:95]
	v_lshl_add_u64 v[92:93], v[154:155], 0, v[90:91]
	global_load_dwordx4 v[132:135], v[88:89], off
	global_load_dwordx4 v[136:139], v[92:93], off
	v_lshl_add_u64 v[88:89], v[156:157], 0, v[90:91]
	global_load_dwordx4 v[140:143], v[94:95], off
	global_load_dwordx4 v[144:147], v[88:89], off
.Lmy_ldskip_1:
	s_add_i32 s15, s0, 0
	s_add_i32 s0, s15, 0xc000
	v_add_u32_e32 v2, s0, v171
	ds_read_b128 v[68:71], v2 offset:0
	ds_read_b128 v[72:75], v2 offset:0x2000
	v_add_u32_e32 v76, s0, v172
	ds_read_b128 v[182:185], v76 offset:0
	ds_read_b128 v[186:189], v76 offset:0x2000
	v_add_u32_e32 v77, s0, v173
	ds_read_b128 v[190:193], v77 offset:0
	ds_read_b128 v[194:197], v77 offset:0x2000
	v_add_u32_e32 v78, s0, v174
	ds_read_b128 v[198:201], v78 offset:0
	ds_read_b128 v[202:205], v78 offset:0x2000
	s_nop 0
	s_waitcnt lgkmcnt(0)
	ds_read_b128 v[206:209], v2 offset:0x80
	ds_read_b128 v[210:213], v2 offset:0x2080
	ds_read_b128 v[214:217], v76 offset:0x80
	ds_read_b128 v[218:221], v76 offset:0x2080
	ds_read_b128 v[222:225], v77 offset:0x80
	ds_read_b128 v[226:229], v77 offset:0x2080
	ds_read_b128 v[230:233], v78 offset:0x80
	ds_read_b128 v[234:237], v78 offset:0x2080
	s_nop 0
	v_mfma_f32_32x32x16_bf16 v[84:99], v[68:71], v[100:103], 0
	v_mfma_f32_32x32x16_bf16 v[68:83], v[72:75], v[100:103], 0
	v_mfma_f32_32x32x16_bf16 v[84:99], v[182:185], v[104:107], v[84:99]
	v_mfma_f32_32x32x16_bf16 v[68:83], v[186:189], v[104:107], v[68:83]
	v_mfma_f32_32x32x16_bf16 v[84:99], v[190:193], v[108:111], v[84:99]
	v_mfma_f32_32x32x16_bf16 v[68:83], v[194:197], v[108:111], v[68:83]
	v_mfma_f32_32x32x16_bf16 v[84:99], v[198:201], v[112:115], v[84:99]
	v_mfma_f32_32x32x16_bf16 v[68:83], v[202:205], v[112:115], v[68:83]
	s_waitcnt lgkmcnt(0)
	v_mfma_f32_32x32x16_bf16 v[84:99], v[206:209], v[116:119], v[84:99]
	s_add_i32 s0, s12, s13
	s_cmp_ge_i32 s0, s95
	v_mfma_f32_32x32x16_bf16 v[68:83], v[210:213], v[116:119], v[68:83]
	v_mfma_f32_32x32x16_bf16 v[84:99], v[214:217], v[120:123], v[84:99]
	v_mfma_f32_32x32x16_bf16 v[68:83], v[218:221], v[120:123], v[68:83]
	v_mfma_f32_32x32x16_bf16 v[84:99], v[222:225], v[124:127], v[84:99]
	v_mfma_f32_32x32x16_bf16 v[68:83], v[226:229], v[124:127], v[68:83]
	v_mfma_f32_32x32x16_bf16 v[84:99], v[230:233], v[128:131], v[84:99]
	v_mfma_f32_32x32x16_bf16 v[68:83], v[234:237], v[128:131], v[68:83]
	s_cbranch_scc1 .LBB0_3083
	ds_read_b32 v182, v178 offset:0xec
	ds_read_b32 v184, v178 offset:0x6c
	ds_read_b32 v183, v178 offset:0xe8
	ds_read_b32 v185, v178 offset:0x68
	ds_read_b32 v186, v178 offset:0xe4
	ds_read_b32 v188, v178 offset:0x64
	ds_read_b32 v187, v178 offset:0xe0
	ds_read_b32 v189, v178 offset:0x60
	ds_read_b32 v190, v178 offset:0xcc
	ds_read_b32 v192, v178 offset:0x4c
	ds_read_b32 v191, v178 offset:0xc8
	ds_read_b32 v193, v178 offset:0x48
	ds_read_b32 v194, v178 offset:0xc4
	ds_read_b32 v196, v178 offset:0x44
	ds_read_b32 v195, v178 offset:0xc0
	ds_read_b32 v197, v178 offset:64
	ds_read_b32 v198, v178 offset:0xac
	ds_read_b32 v200, v178 offset:44
	ds_read_b32 v199, v178 offset:0xa8
	ds_read_b32 v201, v178 offset:40
	ds_read_b32 v202, v178 offset:0xa4
	ds_read_b32 v204, v178 offset:36
	ds_read_b32 v203, v178 offset:0xa0
	ds_read_b32 v205, v178 offset:32
	ds_read_b32 v206, v178 offset:0x8c
	ds_read_b32 v208, v178 offset:12
	ds_read_b32 v207, v178 offset:0x88
	ds_read_b32 v209, v178 offset:8
	ds_read_b32 v210, v178 offset:0x84
	ds_read_b32 v212, v178 offset:4
	ds_read_b32 v211, v178 offset:0x80
	ds_read_b32 v213, v178 offset:0
	s_nop 0
	s_waitcnt lgkmcnt(0)
	s_nop 8
	v_pk_add_f32 v[98:99], v[98:99], v[210:211]
	v_pk_add_f32 v[96:97], v[96:97], v[206:207]
	v_pk_add_f32 v[94:95], v[94:95], v[202:203]
	v_pk_add_f32 v[92:93], v[92:93], v[198:199]
	v_pk_add_f32 v[90:91], v[90:91], v[194:195]
	v_pk_add_f32 v[88:89], v[88:89], v[190:191]
	v_pk_add_f32 v[86:87], v[86:87], v[186:187]
	v_pk_add_f32 v[84:85], v[84:85], v[182:183]
	v_pk_add_f32 v[82:83], v[82:83], v[212:213]
	v_pk_add_f32 v[80:81], v[80:81], v[208:209]
	v_pk_add_f32 v[78:79], v[78:79], v[204:205]
	v_pk_add_f32 v[76:77], v[76:77], v[200:201]
	v_pk_add_f32 v[74:75], v[74:75], v[196:197]
	v_pk_add_f32 v[72:73], v[72:73], v[192:193]
	v_pk_add_f32 v[70:71], v[70:71], v[188:189]
	v_pk_add_f32 v[68:69], v[68:69], v[184:185]

; #define LAS __attribute__((address_space(3)))
; #define SBAR() __builtin_amdgcn_sched_barrier(0)
; __device__ __forceinline__ int v_st(int k, int c) { const int kk = (k & ~0xC) | ((k & 4) << 1) | ((k & 8) >> 1); return ((kk >> 3) * 4 + (c >> 5)) * 512 + ((kk & 7) * 32 + (c & 31)) * 2; }
; __device__ __forceinline__ void pv_tile(f32x16* o, int vb, bf16x8 pa0, bf16x8 pa1, bf16x8 pa2, bf16x8 pa3) {
;     ...
;     PV_D0(0); PV_D0(1); PV_D0(2); PV_D0(3);
;     ...
; }
; __device__ __forceinline__ void pack_p(const f32x16& p0, const f32x16& p1, bf16x8& pa0, bf16x8& pa1, bf16x8& pa2, bf16x8& pa3) {
;     ...
;     PK4(p0, 0, pa0); PK4(p0, 8, pa1); PK4(p1, 0, pa2); PK4(p1, 8, pa3);
;     ...
; }
; __device__ __forceinline__ float half_swap_max(float v) { auto rr = __builtin_amdgcn_permlane32_swap(__float_as_uint(v), __float_as_uint(v), false, false); return fmaxf(__uint_as_float(rr[0]), __uint_as_float(rr[1])); }
; __device__ __forceinline__ float half_swap_sum(float v) { auto rr = __builtin_amdgcn_permlane32_swap(__float_as_uint(v), __float_as_uint(v), false, false); return __uint_as_float(rr[0]) + __uint_as_float(rr[1]); }
; __device__ __forceinline__ void tile_write(const TileStage& T, LAS unsigned char* lds, int kbuf, int vbuf, int sr, int sc) {
;     const int kws = KSWZ(sr, sc * 2);
;     *(LAS bf16x8*)(lds + AT_K + kbuf * SHM_T + kws) = T.k0; *(LAS bf16x8*)(lds + AT_K + kbuf * SHM_T + kws + 32 * 256) = T.k1;
;     *(LAS bf16x8*)(lds + AT_V + vbuf * SHM_T + v_st(sr, sc)) = T.v0; *(LAS bf16x8*)(lds + AT_V + vbuf * SHM_T + v_st(32 + sr, sc)) = T.v1;
; }
; template <int MODE>
; __device__ __forceinline__ void attn_branch(Frame& F, const bf16_t* Kp, const bf16_t* Vp, int j_lo, int j_hi, int sb, const bf16x8* qr, unsigned smask, f32x16* o, float& l_out) {
;     ...
;         float ps = 0.f;
; #pragma unroll
;         for (int r = 0; r < 16; ++r) { C0[r] = __builtin_amdgcn_exp2f(C0[r] - m_reg); C1[r] = __builtin_amdgcn_exp2f(C1[r] - m_reg); ps += C0[r] + C1[r]; }
;         ps = half_swap_sum(ps);
;         l_reg = l_reg * alpha + ps;
;         bf16x8 pa0, pa1, pa2, pa3; pack_p(C0, C1, pa0, pa1, pa2, pa3);
;         if (t + 2 < NT) tile_load(T, Kp, Vp, (j + 2) * 64, sr, sc);
;         SBAR();
;         pv_tile(o, vb0 + vs * SHM_T, pa0, pa1, pa2, pa3);
;         if (t + 2 < NT) tile_write(T, lds, t & 1, vs == 0 ? 2 : vs - 1, sr, sc);
.LBB0_3090:
	v_sub_f32_e32 v84, v84, v2
	v_sub_f32_e32 v68, v68, v2
	v_exp_f32_e32 v159, v84
	v_exp_f32_e32 v182, v68
	v_sub_f32_e32 v68, v85, v2
	v_sub_f32_e32 v69, v69, v2
	v_exp_f32_e32 v68, v68
	v_exp_f32_e32 v183, v69
	v_add_f32_e32 v69, v159, v182
	v_sub_f32_e32 v85, v86, v2
	v_sub_f32_e32 v70, v70, v2
	v_add_f32_e32 v69, 0, v69
	v_add_f32_e32 v84, v68, v183
	v_exp_f32_e32 v86, v85
	v_exp_f32_e32 v184, v70
	v_sub_f32_e32 v70, v87, v2
	v_sub_f32_e32 v71, v71, v2
	v_exp_f32_e32 v70, v70
	v_exp_f32_e32 v87, v71
	v_add_f32_e32 v69, v84, v69
	v_sub_f32_e32 v84, v88, v2
	v_sub_f32_e32 v72, v72, v2
	v_exp_f32_e32 v88, v84
	v_exp_f32_e32 v185, v72
	v_sub_f32_e32 v72, v89, v2
	v_sub_f32_e32 v73, v73, v2
	v_exp_f32_e32 v72, v72
	v_exp_f32_e32 v89, v73
	v_sub_f32_e32 v73, v90, v2
	v_sub_f32_e32 v74, v74, v2
	v_add_f32_e32 v71, v86, v184
	v_exp_f32_e32 v73, v73
	v_exp_f32_e32 v90, v74
	v_sub_f32_e32 v74, v91, v2
	v_sub_f32_e32 v75, v75, v2
	v_add_f32_e32 v69, v71, v69
	v_add_f32_e32 v71, v70, v87
	v_exp_f32_e32 v74, v74
	v_exp_f32_e32 v91, v75
	v_sub_f32_e32 v75, v92, v2
	v_sub_f32_e32 v76, v76, v2
	v_add_f32_e32 v69, v71, v69
	v_add_f32_e32 v71, v88, v185
	v_exp_f32_e32 v75, v75
	v_exp_f32_e32 v76, v76
	v_sub_f32_e32 v84, v93, v2
	v_sub_f32_e32 v77, v77, v2
	v_add_f32_e32 v69, v71, v69
	v_add_f32_e32 v71, v72, v89
	v_exp_f32_e32 v92, v84
	v_exp_f32_e32 v77, v77
	v_sub_f32_e32 v84, v94, v2
	v_sub_f32_e32 v78, v78, v2
	v_add_f32_e32 v69, v71, v69
	v_add_f32_e32 v71, v73, v90
	v_exp_f32_e32 v93, v84
	v_exp_f32_e32 v78, v78
	v_sub_f32_e32 v84, v95, v2
	v_sub_f32_e32 v79, v79, v2
	v_add_f32_e32 v69, v71, v69
	v_add_f32_e32 v71, v74, v91
	v_exp_f32_e32 v94, v84
	v_exp_f32_e32 v79, v79
	v_sub_f32_e32 v84, v96, v2
	v_sub_f32_e32 v80, v80, v2
	v_add_f32_e32 v69, v71, v69
	v_add_f32_e32 v71, v75, v76
	v_exp_f32_e32 v95, v84
	v_exp_f32_e32 v96, v80
	v_sub_f32_e32 v80, v97, v2
	v_sub_f32_e32 v81, v81, v2
	v_add_f32_e32 v69, v71, v69
	v_add_f32_e32 v71, v92, v77
	v_exp_f32_e32 v80, v80
	v_exp_f32_e32 v97, v81
	v_sub_f32_e32 v81, v98, v2
	v_sub_f32_e32 v82, v82, v2
	v_add_f32_e32 v69, v71, v69
	v_add_f32_e32 v71, v93, v78
	v_exp_f32_e32 v81, v81
	v_exp_f32_e32 v98, v82
	v_sub_f32_e32 v82, v99, v2
	v_sub_f32_e32 v83, v83, v2
	v_add_f32_e32 v69, v71, v69
	v_add_f32_e32 v71, v94, v79
	v_exp_f32_e32 v82, v82
	v_exp_f32_e32 v99, v83
	v_add_f32_e32 v69, v71, v69
	v_add_f32_e32 v71, v95, v96
	v_add_f32_e32 v69, v71, v69
	v_add_f32_e32 v71, v80, v97
	v_add_f32_e32 v69, v71, v69
	v_add_f32_e32 v71, v81, v98
	v_add_f32_e32 v69, v71, v69
	v_add_f32_e32 v71, v82, v99
	v_add_f32_e32 v84, v71, v69
	v_mov_b32_e32 v85, v84
	v_cvt_pk_bf16_f32 v68, v159, v68
	v_cvt_pk_bf16_f32 v69, v86, v70
	v_cvt_pk_bf16_f32 v70, v88, v72
	v_cvt_pk_bf16_f32 v71, v73, v74
	v_cvt_pk_bf16_f32 v72, v75, v92
	v_cvt_pk_bf16_f32 v73, v93, v94
	v_cvt_pk_bf16_f32 v74, v95, v80
	v_cvt_pk_bf16_f32 v75, v81, v82
	v_cvt_pk_bf16_f32 v80, v182, v183
	v_cvt_pk_bf16_f32 v81, v184, v87
	v_cvt_pk_bf16_f32 v82, v185, v89
	v_cvt_pk_bf16_f32 v83, v90, v91
	v_cvt_pk_bf16_f32 v76, v76, v77
	v_cvt_pk_bf16_f32 v77, v78, v79
	v_cvt_pk_bf16_f32 v78, v96, v97
	v_cvt_pk_bf16_f32 v79, v98, v99
	s_cmp_le_i32 s7, s6
	s_nop 0
	v_permlane32_swap_b32_e32 v84, v85
	v_permlane32_swap_b32_e32 v68, v70
	v_permlane32_swap_b32_e32 v69, v71
	v_permlane32_swap_b32_e32 v72, v74
	v_permlane32_swap_b32_e32 v73, v75
	v_permlane32_swap_b32_e32 v80, v82
	v_permlane32_swap_b32_e32 v81, v83
	v_permlane32_swap_b32_e32 v76, v78
	s_cselect_b64 s[0:1], -1, 0
	s_cmp_gt_i32 s7, s6
	v_permlane32_swap_b32_e32 v77, v79
	s_cbranch_scc1 .LBB0_3092
.LBB0_3092:
	s_lshl_b32 s16, s14, 14
	v_add_u32_e32 v98, s16, v177
	ds_read_b64_tr_b16 v[86:87], v98 offset:0
	ds_read_b64_tr_b16 v[88:89], v98 offset:0x800
	ds_read_b64_tr_b16 v[90:91], v98 offset:0x1000
	ds_read_b64_tr_b16 v[92:93], v98 offset:0x1800
	ds_read_b64_tr_b16 v[94:95], v98 offset:0x2000
	ds_read_b64_tr_b16 v[96:97], v98 offset:0x2800
	ds_read_b64_tr_b16 v[182:183], v98 offset:0x3000
	ds_read_b64_tr_b16 v[184:185], v98 offset:0x3800
	s_waitcnt lgkmcnt(0)
	s_nop 0
	v_mfma_f32_32x32x16_bf16 v[52:67], v[68:71], v[86:89], v[52:67]
	ds_read_b64_tr_b16 v[86:87], v98 offset:0x200
	ds_read_b64_tr_b16 v[88:89], v98 offset:0xa00
	v_mfma_f32_32x32x16_bf16 v[52:67], v[72:75], v[90:93], v[52:67]
	ds_read_b64_tr_b16 v[90:91], v98 offset:0x1200
	ds_read_b64_tr_b16 v[92:93], v98 offset:0x1a00
	v_mfma_f32_32x32x16_bf16 v[52:67], v[80:83], v[94:97], v[52:67]
	ds_read_b64_tr_b16 v[94:95], v98 offset:0x2200
	ds_read_b64_tr_b16 v[96:97], v98 offset:0x2a00
	v_mfma_f32_32x32x16_bf16 v[52:67], v[76:79], v[182:185], v[52:67]
	ds_read_b64_tr_b16 v[182:183], v98 offset:0x3200
	ds_read_b64_tr_b16 v[184:185], v98 offset:0x3a00
	s_waitcnt lgkmcnt(0)
	v_mfma_f32_32x32x16_bf16 v[36:51], v[68:71], v[86:89], v[36:51]
	ds_read_b64_tr_b16 v[86:87], v98 offset:0x400
	ds_read_b64_tr_b16 v[88:89], v98 offset:0xc00
	v_mfma_f32_32x32x16_bf16 v[36:51], v[72:75], v[90:93], v[36:51]
	ds_read_b64_tr_b16 v[90:91], v98 offset:0x1400
	ds_read_b64_tr_b16 v[92:93], v98 offset:0x1c00
	v_mfma_f32_32x32x16_bf16 v[36:51], v[80:83], v[94:97], v[36:51]
	ds_read_b64_tr_b16 v[94:95], v98 offset:0x2400
	ds_read_b64_tr_b16 v[96:97], v98 offset:0x2c00
	v_mfma_f32_32x32x16_bf16 v[36:51], v[76:79], v[182:185], v[36:51]
	ds_read_b64_tr_b16 v[182:183], v98 offset:0x3400
	ds_read_b64_tr_b16 v[184:185], v98 offset:0x3c00
	s_waitcnt lgkmcnt(0)
	v_mfma_f32_32x32x16_bf16 v[20:35], v[68:71], v[86:89], v[20:35]
	ds_read_b64_tr_b16 v[86:87], v98 offset:0x600
	ds_read_b64_tr_b16 v[88:89], v98 offset:0xe00
	v_mfma_f32_32x32x16_bf16 v[20:35], v[72:75], v[90:93], v[20:35]
	ds_read_b64_tr_b16 v[90:91], v98 offset:0x1600
	ds_read_b64_tr_b16 v[92:93], v98 offset:0x1e00
	v_mfma_f32_32x32x16_bf16 v[20:35], v[80:83], v[94:97], v[20:35]
	ds_read_b64_tr_b16 v[94:95], v98 offset:0x2600
	ds_read_b64_tr_b16 v[96:97], v98 offset:0x2e00
	v_mfma_f32_32x32x16_bf16 v[20:35], v[76:79], v[182:185], v[20:35]
	ds_read_b64_tr_b16 v[182:183], v98 offset:0x3600
	ds_read_b64_tr_b16 v[184:185], v98 offset:0x3e00
	s_waitcnt lgkmcnt(0)
	v_mfma_f32_32x32x16_bf16 v[4:19], v[68:71], v[86:89], v[4:19]
	s_andn2_b64 vcc, exec, s[0:1]
	v_mfma_f32_32x32x16_bf16 v[4:19], v[72:75], v[90:93], v[4:19]
	v_mfma_f32_32x32x16_bf16 v[4:19], v[80:83], v[94:97], v[4:19]
	v_mfma_f32_32x32x16_bf16 v[4:19], v[76:79], v[182:185], v[4:19]
	s_cbranch_vccnz .LBB0_3094
	s_addk_i32 s16, 0xc000
	s_cmp_lg_u32 s14, 0
	s_cselect_b32 s0, s16, 0x8000
	v_add_u32_e32 v68, s0, v169
	v_add3_u32 v70, s15, v160, v161
	v_add3_u32 v69, v68, v170, v168
	v_add3_u32 v68, v68, v167, v168
	s_waitcnt vmcnt(3)
	ds_write_b128 v70, v[132:135] offset:49152
	s_waitcnt vmcnt(2)
	ds_write_b128 v70, v[136:139] offset:57344
	s_waitcnt vmcnt(1)
	ds_write_b128 v68, v[140:143]
	s_waitcnt vmcnt(0)
	ds_write_b128 v69, v[144:147]

; __device__ __forceinline__ void qkt(f32x16& p0, f32x16& p1, const LAS unsigned char* Kt, int r32, int hi, const bf16x8* qr, float init) {
;     f32x16 zi;
; #pragma unroll
;     for (int r = 0; r < 16; ++r) zi[r] = init;
;     const int kt = (int)(uintptr_t)Kt;
;     const int a0 = kt + KSWZ(r32, (0 * 16 + hi * 8) * 2), a1 = kt + KSWZ(r32, (1 * 16 + hi * 8) * 2), a2 = kt + KSWZ(r32, (2 * 16 + hi * 8) * 2), a3 = kt + KSWZ(r32, (3 * 16 + hi * 8) * 2);
;     ...
;     bf16x8 f0, f1, f2, f3, g0, g1, g2, g3, f4, f5, f6, f7, g4, g5, g6, g7;
;     DSR128(f0, a0, 0); DSR128(g0, a0, 8192); DSR128(f1, a1, 0); DSR128(g1, a1, 8192); DSR128(f2, a2, 0); DSR128(g2, a2, 8192); DSR128(f3, a3, 0); DSR128(g3, a3, 8192);
;     asm volatile("s_waitcnt lgkmcnt(0)" : "+v"(f0), "+v"(g0), "+v"(f1), "+v"(g1), "+v"(f2), "+v"(g2), "+v"(f3), "+v"(g3) :: "memory");
;     DSR128(f4, a0, 128); DSR128(g4, a0, 8320); DSR128(f5, a1, 128); DSR128(g5, a1, 8320); DSR128(f6, a2, 128); DSR128(g6, a2, 8320); DSR128(f7, a3, 128); DSR128(g7, a3, 8320);
;     SBAR();
;     p0 = __builtin_amdgcn_mfma_f32_32x32x16_bf16(f0, qr[0], zi, 0, 0, 0); p1 = __builtin_amdgcn_mfma_f32_32x32x16_bf16(g0, qr[0], zi, 0, 0, 0);
;     p0 = __builtin_amdgcn_mfma_f32_32x32x16_bf16(f1, qr[1], p0, 0, 0, 0); p1 = __builtin_amdgcn_mfma_f32_32x32x16_bf16(g1, qr[1], p1, 0, 0, 0);
;     p0 = __builtin_amdgcn_mfma_f32_32x32x16_bf16(f2, qr[2], p0, 0, 0, 0); p1 = __builtin_amdgcn_mfma_f32_32x32x16_bf16(g2, qr[2], p1, 0, 0, 0);
;     p0 = __builtin_amdgcn_mfma_f32_32x32x16_bf16(f3, qr[3], p0, 0, 0, 0); p1 = __builtin_amdgcn_mfma_f32_32x32x16_bf16(g3, qr[3], p1, 0, 0, 0);
;     asm volatile("s_waitcnt lgkmcnt(0)" : "+v"(f4), "+v"(g4), "+v"(f5), "+v"(g5), "+v"(f6), "+v"(g6), "+v"(f7), "+v"(g7) :: "memory");
;     SBAR();
;     p0 = __builtin_amdgcn_mfma_f32_32x32x16_bf16(f4, qr[4], p0, 0, 0, 0); p1 = __builtin_amdgcn_mfma_f32_32x32x16_bf16(g4, qr[4], p1, 0, 0, 0);
;     p0 = __builtin_amdgcn_mfma_f32_32x32x16_bf16(f5, qr[5], p0, 0, 0, 0); p1 = __builtin_amdgcn_mfma_f32_32x32x16_bf16(g5, qr[5], p1, 0, 0, 0);
;     p0 = __builtin_amdgcn_mfma_f32_32x32x16_bf16(f6, qr[6], p0, 0, 0, 0); p1 = __builtin_amdgcn_mfma_f32_32x32x16_bf16(g6, qr[6], p1, 0, 0, 0);
;     p0 = __builtin_amdgcn_mfma_f32_32x32x16_bf16(f7, qr[7], p0, 0, 0, 0); p1 = __builtin_amdgcn_mfma_f32_32x32x16_bf16(g7, qr[7], p1, 0, 0, 0);
;     ...
; }
.LBB0_3502:
	s_and_b32 s0, s8, 0x4000
	s_cmp_gt_i32 s11, s6
	s_cbranch_scc1 .Lmy_ldskip_2
	v_subrev_u32_e32 v94, 32, v156
	v_ashrrev_i32_e32 v95, 31, v94
	v_lshlrev_b64 v[94:95], 8, v[94:95]
	v_mov_b32_e32 v96, v156
	v_ashrrev_i32_e32 v97, 31, v156
	v_lshl_add_u64 v[88:89], v[152:153], 0, v[94:95]
	v_lshlrev_b64 v[90:91], 8, v[96:97]
	v_lshl_add_u64 v[94:95], v[154:155], 0, v[94:95]
	v_lshl_add_u64 v[92:93], v[152:153], 0, v[90:91]
	global_load_dwordx4 v[132:135], v[88:89], off
	global_load_dwordx4 v[136:139], v[92:93], off
	v_lshl_add_u64 v[88:89], v[154:155], 0, v[90:91]
	global_load_dwordx4 v[140:143], v[94:95], off
	global_load_dwordx4 v[144:147], v[88:89], off
.Lmy_ldskip_2:
	s_add_i32 s12, s0, 0
	s_add_i32 s0, s12, 0xc000
	v_bfe_u32 v2, v151, s11, 1
	v_cmp_eq_u32_e32 vcc, 0, v2
	v_add_u32_e32 v2, s0, v170
	ds_read_b128 v[180:183], v2 offset:0
	ds_read_b128 v[184:187], v2 offset:0x2000
	v_add_u32_e32 v84, s0, v171
	ds_read_b128 v[188:191], v84 offset:0
	ds_read_b128 v[192:195], v84 offset:0x2000
	v_add_u32_e32 v85, s0, v172
	ds_read_b128 v[196:199], v85 offset:0
	ds_read_b128 v[200:203], v85 offset:0x2000
	v_add_u32_e32 v86, s0, v173
	ds_read_b128 v[204:207], v86 offset:0
	ds_read_b128 v[208:211], v86 offset:0x2000
	v_cndmask_b32_e32 v68, 0, v163, vcc
	s_waitcnt lgkmcnt(0)
	ds_read_b128 v[212:215], v2 offset:0x80
	ds_read_b128 v[216:219], v2 offset:0x2080
	ds_read_b128 v[220:223], v84 offset:0x80
	ds_read_b128 v[224:227], v84 offset:0x2080
	ds_read_b128 v[228:231], v85 offset:0x80
	ds_read_b128 v[232:235], v85 offset:0x2080
	ds_read_b128 v[236:239], v86 offset:0x80
	ds_read_b128 v[240:243], v86 offset:0x2080
	v_mov_b32_e32 v69, v68
	v_mov_b32_e32 v70, v68
	v_mov_b32_e32 v71, v68
	v_mov_b32_e32 v72, v68
	v_mov_b32_e32 v73, v68
	v_mov_b32_e32 v74, v68
	v_mov_b32_e32 v75, v68
	v_mov_b32_e32 v76, v68
	v_mov_b32_e32 v77, v68
	v_mov_b32_e32 v78, v68
	v_mov_b32_e32 v79, v68
	v_mov_b32_e32 v80, v68
	v_mov_b32_e32 v81, v68
	v_mov_b32_e32 v82, v68
	v_mov_b32_e32 v83, v68
	s_nop 1
	v_mfma_f32_32x32x16_bf16 v[84:99], v[180:183], v[100:103], v[68:83]
	v_mfma_f32_32x32x16_bf16 v[68:83], v[184:187], v[100:103], v[68:83]
	v_mfma_f32_32x32x16_bf16 v[84:99], v[188:191], v[104:107], v[84:99]
	v_mfma_f32_32x32x16_bf16 v[68:83], v[192:195], v[104:107], v[68:83]
	v_mfma_f32_32x32x16_bf16 v[84:99], v[196:199], v[108:111], v[84:99]
	v_mfma_f32_32x32x16_bf16 v[68:83], v[200:203], v[108:111], v[68:83]
	v_mfma_f32_32x32x16_bf16 v[84:99], v[204:207], v[112:115], v[84:99]
	v_mfma_f32_32x32x16_bf16 v[68:83], v[208:211], v[112:115], v[68:83]
	s_waitcnt lgkmcnt(0)
	v_mfma_f32_32x32x16_bf16 v[84:99], v[212:215], v[116:119], v[84:99]
	s_cmp_ge_i32 s9, s95
	v_mfma_f32_32x32x16_bf16 v[68:83], v[216:219], v[116:119], v[68:83]
	v_mfma_f32_32x32x16_bf16 v[84:99], v[220:223], v[120:123], v[84:99]
	v_mfma_f32_32x32x16_bf16 v[68:83], v[224:227], v[120:123], v[68:83]
	v_mfma_f32_32x32x16_bf16 v[84:99], v[228:231], v[124:127], v[84:99]
	v_mfma_f32_32x32x16_bf16 v[68:83], v[232:235], v[124:127], v[68:83]
	v_mfma_f32_32x32x16_bf16 v[84:99], v[236:239], v[128:131], v[84:99]
	v_mfma_f32_32x32x16_bf16 v[68:83], v[240:243], v[128:131], v[68:83]
	s_cbranch_scc1 .LBB0_3504
	ds_read_b32 v180, v177 offset:0xec
	ds_read_b32 v182, v177 offset:0x6c
	ds_read_b32 v181, v177 offset:0xe8
	ds_read_b32 v183, v177 offset:0x68
	ds_read_b32 v184, v177 offset:0xe4
	ds_read_b32 v186, v177 offset:0x64
	ds_read_b32 v185, v177 offset:0xe0
	ds_read_b32 v187, v177 offset:0x60
	ds_read_b32 v188, v177 offset:0xcc
	ds_read_b32 v190, v177 offset:0x4c
	ds_read_b32 v189, v177 offset:0xc8
	ds_read_b32 v191, v177 offset:0x48
	ds_read_b32 v192, v177 offset:0xc4
	ds_read_b32 v194, v177 offset:0x44
	ds_read_b32 v193, v177 offset:0xc0
	ds_read_b32 v195, v177 offset:64
	ds_read_b32 v196, v177 offset:0xac
	ds_read_b32 v198, v177 offset:44
	ds_read_b32 v197, v177 offset:0xa8
	ds_read_b32 v199, v177 offset:40
	ds_read_b32 v200, v177 offset:0xa4
	ds_read_b32 v202, v177 offset:36
	ds_read_b32 v201, v177 offset:0xa0
	ds_read_b32 v203, v177 offset:32
	ds_read_b32 v204, v177 offset:0x8c
	ds_read_b32 v206, v177 offset:12
	ds_read_b32 v205, v177 offset:0x88
	ds_read_b32 v207, v177 offset:8
	ds_read_b32 v208, v177 offset:0x84
	ds_read_b32 v210, v177 offset:4
	ds_read_b32 v209, v177 offset:0x80
	ds_read_b32 v211, v177 offset:0
	s_nop 0
	s_waitcnt lgkmcnt(0)
	s_nop 8
	v_pk_add_f32 v[98:99], v[98:99], v[208:209]
	v_pk_add_f32 v[96:97], v[96:97], v[204:205]
	v_pk_add_f32 v[94:95], v[94:95], v[200:201]
	v_pk_add_f32 v[92:93], v[92:93], v[196:197]
	v_pk_add_f32 v[90:91], v[90:91], v[192:193]
	v_pk_add_f32 v[88:89], v[88:89], v[188:189]
	v_pk_add_f32 v[86:87], v[86:87], v[184:185]
	v_pk_add_f32 v[84:85], v[84:85], v[180:181]
	v_pk_add_f32 v[82:83], v[82:83], v[210:211]
	v_pk_add_f32 v[80:81], v[80:81], v[206:207]
	v_pk_add_f32 v[78:79], v[78:79], v[202:203]
	v_pk_add_f32 v[76:77], v[76:77], v[198:199]
	v_pk_add_f32 v[74:75], v[74:75], v[194:195]
	v_pk_add_f32 v[72:73], v[72:73], v[190:191]
	v_pk_add_f32 v[70:71], v[70:71], v[186:187]
	v_pk_add_f32 v[68:69], v[68:69], v[182:183]

; #define LAS __attribute__((address_space(3)))
; #define SBAR() __builtin_amdgcn_sched_barrier(0)
; __device__ __forceinline__ int v_st(int k, int c) { const int kk = (k & ~0xC) | ((k & 4) << 1) | ((k & 8) >> 1); return ((kk >> 3) * 4 + (c >> 5)) * 512 + ((kk & 7) * 32 + (c & 31)) * 2; }
; __device__ __forceinline__ void pv_tile(f32x16* o, int vb, bf16x8 pa0, bf16x8 pa1, bf16x8 pa2, bf16x8 pa3) {
;     ...
;     PV_D0(0); PV_D0(1); PV_D0(2); PV_D0(3);
;     ...
; }
; __device__ __forceinline__ void pack_p(const f32x16& p0, const f32x16& p1, bf16x8& pa0, bf16x8& pa1, bf16x8& pa2, bf16x8& pa3) {
;     ...
;     PK4(p0, 0, pa0); PK4(p0, 8, pa1); PK4(p1, 0, pa2); PK4(p1, 8, pa3);
;     ...
; }
; __device__ __forceinline__ float half_swap_max(float v) { auto rr = __builtin_amdgcn_permlane32_swap(__float_as_uint(v), __float_as_uint(v), false, false); return fmaxf(__uint_as_float(rr[0]), __uint_as_float(rr[1])); }
; __device__ __forceinline__ float half_swap_sum(float v) { auto rr = __builtin_amdgcn_permlane32_swap(__float_as_uint(v), __float_as_uint(v), false, false); return __uint_as_float(rr[0]) + __uint_as_float(rr[1]); }
; __device__ __forceinline__ void tile_write(const TileStage& T, LAS unsigned char* lds, int kbuf, int vbuf, int sr, int sc) {
;     const int kws = KSWZ(sr, sc * 2);
;     *(LAS bf16x8*)(lds + AT_K + kbuf * SHM_T + kws) = T.k0; *(LAS bf16x8*)(lds + AT_K + kbuf * SHM_T + kws + 32 * 256) = T.k1;
;     *(LAS bf16x8*)(lds + AT_V + vbuf * SHM_T + v_st(sr, sc)) = T.v0; *(LAS bf16x8*)(lds + AT_V + vbuf * SHM_T + v_st(32 + sr, sc)) = T.v1;
; }
; template <int MODE>
; __device__ __forceinline__ void attn_branch(Frame& F, const bf16_t* Kp, const bf16_t* Vp, int j_lo, int j_hi, int sb, const bf16x8* qr, unsigned smask, f32x16* o, float& l_out) {
;     ...
;         float ps = 0.f;
; #pragma unroll
;         for (int r = 0; r < 16; ++r) { C0[r] = __builtin_amdgcn_exp2f(C0[r] - m_reg); C1[r] = __builtin_amdgcn_exp2f(C1[r] - m_reg); ps += C0[r] + C1[r]; }
;         ps = half_swap_sum(ps);
;         l_reg = l_reg * alpha + ps;
;         bf16x8 pa0, pa1, pa2, pa3; pack_p(C0, C1, pa0, pa1, pa2, pa3);
;         if (t + 2 < NT) tile_load(T, Kp, Vp, (j + 2) * 64, sr, sc);
;         SBAR();
;         pv_tile(o, vb0 + vs * SHM_T, pa0, pa1, pa2, pa3);
;         if (t + 2 < NT) tile_write(T, lds, t & 1, vs == 0 ? 2 : vs - 1, sr, sc);
.LBB0_3511:
	v_sub_f32_e32 v84, v84, v2
	v_sub_f32_e32 v68, v68, v2
	v_exp_f32_e32 v157, v84
	v_exp_f32_e32 v181, v68
	v_sub_f32_e32 v68, v85, v2
	v_sub_f32_e32 v69, v69, v2
	v_exp_f32_e32 v68, v68
	v_exp_f32_e32 v182, v69
	v_add_f32_e32 v69, v157, v181
	v_sub_f32_e32 v85, v86, v2
	v_sub_f32_e32 v70, v70, v2
	v_add_f32_e32 v69, 0, v69
	v_add_f32_e32 v84, v68, v182
	v_exp_f32_e32 v86, v85
	v_exp_f32_e32 v183, v70
	v_sub_f32_e32 v70, v87, v2
	v_sub_f32_e32 v71, v71, v2
	v_exp_f32_e32 v70, v70
	v_exp_f32_e32 v87, v71
	v_add_f32_e32 v69, v84, v69
	v_sub_f32_e32 v84, v88, v2
	v_sub_f32_e32 v72, v72, v2
	v_exp_f32_e32 v88, v84
	v_exp_f32_e32 v184, v72
	v_sub_f32_e32 v72, v89, v2
	v_sub_f32_e32 v73, v73, v2
	v_exp_f32_e32 v72, v72
	v_exp_f32_e32 v89, v73
	v_sub_f32_e32 v73, v90, v2
	v_sub_f32_e32 v74, v74, v2
	v_add_f32_e32 v71, v86, v183
	v_exp_f32_e32 v73, v73
	v_exp_f32_e32 v90, v74
	v_sub_f32_e32 v74, v91, v2
	v_sub_f32_e32 v75, v75, v2
	v_add_f32_e32 v69, v71, v69
	v_add_f32_e32 v71, v70, v87
	v_exp_f32_e32 v74, v74
	v_exp_f32_e32 v91, v75
	v_sub_f32_e32 v75, v92, v2
	v_sub_f32_e32 v76, v76, v2
	v_add_f32_e32 v69, v71, v69
	v_add_f32_e32 v71, v88, v184
	v_exp_f32_e32 v75, v75
	v_exp_f32_e32 v76, v76
	v_sub_f32_e32 v84, v93, v2
	v_sub_f32_e32 v77, v77, v2
	v_add_f32_e32 v69, v71, v69
	v_add_f32_e32 v71, v72, v89
	v_exp_f32_e32 v92, v84
	v_exp_f32_e32 v77, v77
	v_sub_f32_e32 v84, v94, v2
	v_sub_f32_e32 v78, v78, v2
	v_add_f32_e32 v69, v71, v69
	v_add_f32_e32 v71, v73, v90
	v_exp_f32_e32 v93, v84
	v_exp_f32_e32 v78, v78
	v_sub_f32_e32 v84, v95, v2
	v_sub_f32_e32 v79, v79, v2
	v_add_f32_e32 v69, v71, v69
	v_add_f32_e32 v71, v74, v91
	v_exp_f32_e32 v94, v84
	v_exp_f32_e32 v79, v79
	v_sub_f32_e32 v84, v96, v2
	v_sub_f32_e32 v80, v80, v2
	v_add_f32_e32 v69, v71, v69
	v_add_f32_e32 v71, v75, v76
	v_exp_f32_e32 v95, v84
	v_exp_f32_e32 v96, v80
	v_sub_f32_e32 v80, v97, v2
	v_sub_f32_e32 v81, v81, v2
	v_add_f32_e32 v69, v71, v69
	v_add_f32_e32 v71, v92, v77
	v_exp_f32_e32 v80, v80
	v_exp_f32_e32 v97, v81
	v_sub_f32_e32 v81, v98, v2
	v_sub_f32_e32 v82, v82, v2
	v_add_f32_e32 v69, v71, v69
	v_add_f32_e32 v71, v93, v78
	v_exp_f32_e32 v81, v81
	v_exp_f32_e32 v98, v82
	v_sub_f32_e32 v82, v99, v2
	v_sub_f32_e32 v83, v83, v2
	v_add_f32_e32 v69, v71, v69
	v_add_f32_e32 v71, v94, v79
	v_exp_f32_e32 v82, v82
	v_exp_f32_e32 v99, v83
	v_add_f32_e32 v69, v71, v69
	v_add_f32_e32 v71, v95, v96
	v_add_f32_e32 v69, v71, v69
	v_add_f32_e32 v71, v80, v97
	v_add_f32_e32 v69, v71, v69
	v_add_f32_e32 v71, v81, v98
	v_add_f32_e32 v69, v71, v69
	v_add_f32_e32 v71, v82, v99
	v_add_f32_e32 v84, v71, v69
	v_mov_b32_e32 v85, v84
	v_cvt_pk_bf16_f32 v68, v157, v68
	v_cvt_pk_bf16_f32 v69, v86, v70
	v_cvt_pk_bf16_f32 v70, v88, v72
	v_cvt_pk_bf16_f32 v71, v73, v74
	v_cvt_pk_bf16_f32 v72, v75, v92
	v_cvt_pk_bf16_f32 v73, v93, v94
	v_cvt_pk_bf16_f32 v74, v95, v80
	v_cvt_pk_bf16_f32 v75, v81, v82
	v_cvt_pk_bf16_f32 v80, v181, v182
	v_cvt_pk_bf16_f32 v81, v183, v87
	v_cvt_pk_bf16_f32 v82, v184, v89
	v_cvt_pk_bf16_f32 v83, v90, v91
	v_cvt_pk_bf16_f32 v76, v76, v77
	v_cvt_pk_bf16_f32 v77, v78, v79
	v_cvt_pk_bf16_f32 v78, v96, v97
	v_cvt_pk_bf16_f32 v79, v98, v99
	s_cmp_le_i32 s11, s6
	s_nop 0
	v_permlane32_swap_b32_e32 v84, v85
	v_permlane32_swap_b32_e32 v68, v70
	v_permlane32_swap_b32_e32 v69, v71
	v_permlane32_swap_b32_e32 v72, v74
	v_permlane32_swap_b32_e32 v73, v75
	v_permlane32_swap_b32_e32 v80, v82
	v_permlane32_swap_b32_e32 v81, v83
	v_permlane32_swap_b32_e32 v76, v78
	s_cselect_b64 s[0:1], -1, 0
	s_cmp_gt_i32 s11, s6
	v_permlane32_swap_b32_e32 v77, v79
	s_cbranch_scc1 .LBB0_3513
.LBB0_3513:
	s_lshl_b32 s13, s10, 14
	v_add_u32_e32 v98, s13, v176
	ds_read_b64_tr_b16 v[86:87], v98 offset:0
	ds_read_b64_tr_b16 v[88:89], v98 offset:0x800
	ds_read_b64_tr_b16 v[90:91], v98 offset:0x1000
	ds_read_b64_tr_b16 v[92:93], v98 offset:0x1800
	ds_read_b64_tr_b16 v[94:95], v98 offset:0x2000
	ds_read_b64_tr_b16 v[96:97], v98 offset:0x2800
	ds_read_b64_tr_b16 v[182:183], v98 offset:0x3000
	ds_read_b64_tr_b16 v[184:185], v98 offset:0x3800
	s_waitcnt lgkmcnt(0)
	s_nop 0
	v_mfma_f32_32x32x16_bf16 v[52:67], v[68:71], v[86:89], v[52:67]
	ds_read_b64_tr_b16 v[86:87], v98 offset:0x200
	ds_read_b64_tr_b16 v[88:89], v98 offset:0xa00
	v_mfma_f32_32x32x16_bf16 v[52:67], v[72:75], v[90:93], v[52:67]
	ds_read_b64_tr_b16 v[90:91], v98 offset:0x1200
	ds_read_b64_tr_b16 v[92:93], v98 offset:0x1a00
	v_mfma_f32_32x32x16_bf16 v[52:67], v[80:83], v[94:97], v[52:67]
	ds_read_b64_tr_b16 v[94:95], v98 offset:0x2200
	ds_read_b64_tr_b16 v[96:97], v98 offset:0x2a00
	v_mfma_f32_32x32x16_bf16 v[52:67], v[76:79], v[182:185], v[52:67]
	ds_read_b64_tr_b16 v[182:183], v98 offset:0x3200
	ds_read_b64_tr_b16 v[184:185], v98 offset:0x3a00
	s_waitcnt lgkmcnt(0)
	v_mfma_f32_32x32x16_bf16 v[36:51], v[68:71], v[86:89], v[36:51]
	ds_read_b64_tr_b16 v[86:87], v98 offset:0x400
	ds_read_b64_tr_b16 v[88:89], v98 offset:0xc00
	v_mfma_f32_32x32x16_bf16 v[36:51], v[72:75], v[90:93], v[36:51]
	ds_read_b64_tr_b16 v[90:91], v98 offset:0x1400
	ds_read_b64_tr_b16 v[92:93], v98 offset:0x1c00
	v_mfma_f32_32x32x16_bf16 v[36:51], v[80:83], v[94:97], v[36:51]
	ds_read_b64_tr_b16 v[94:95], v98 offset:0x2400
	ds_read_b64_tr_b16 v[96:97], v98 offset:0x2c00
	v_mfma_f32_32x32x16_bf16 v[36:51], v[76:79], v[182:185], v[36:51]
	ds_read_b64_tr_b16 v[182:183], v98 offset:0x3400
	ds_read_b64_tr_b16 v[184:185], v98 offset:0x3c00
	s_waitcnt lgkmcnt(0)
	v_mfma_f32_32x32x16_bf16 v[20:35], v[68:71], v[86:89], v[20:35]
	ds_read_b64_tr_b16 v[86:87], v98 offset:0x600
	ds_read_b64_tr_b16 v[88:89], v98 offset:0xe00
	v_mfma_f32_32x32x16_bf16 v[20:35], v[72:75], v[90:93], v[20:35]
	ds_read_b64_tr_b16 v[90:91], v98 offset:0x1600
	ds_read_b64_tr_b16 v[92:93], v98 offset:0x1e00
	v_mfma_f32_32x32x16_bf16 v[20:35], v[80:83], v[94:97], v[20:35]
	ds_read_b64_tr_b16 v[94:95], v98 offset:0x2600
	ds_read_b64_tr_b16 v[96:97], v98 offset:0x2e00
	v_mfma_f32_32x32x16_bf16 v[20:35], v[76:79], v[182:185], v[20:35]
	ds_read_b64_tr_b16 v[182:183], v98 offset:0x3600
	ds_read_b64_tr_b16 v[184:185], v98 offset:0x3e00
	s_waitcnt lgkmcnt(0)
	v_mfma_f32_32x32x16_bf16 v[4:19], v[68:71], v[86:89], v[4:19]
	s_andn2_b64 vcc, exec, s[0:1]
	v_mfma_f32_32x32x16_bf16 v[4:19], v[72:75], v[90:93], v[4:19]
	v_mfma_f32_32x32x16_bf16 v[4:19], v[80:83], v[94:97], v[4:19]
	v_mfma_f32_32x32x16_bf16 v[4:19], v[76:79], v[182:185], v[4:19]
	s_cbranch_vccnz .LBB0_3515
	s_addk_i32 s13, 0xc000
	s_cmp_lg_u32 s10, 0
	s_cselect_b32 s0, s13, 0x8000
	v_add_u32_e32 v68, s0, v168
	v_add3_u32 v70, s12, v159, v165
	v_add3_u32 v69, v68, v169, v167
	v_add3_u32 v68, v68, v166, v167
	s_waitcnt vmcnt(3)
	ds_write_b128 v70, v[132:135] offset:49152
	s_waitcnt vmcnt(2)
	ds_write_b128 v70, v[136:139] offset:57344
	s_waitcnt vmcnt(1)
	ds_write_b128 v68, v[140:143]
	s_waitcnt vmcnt(0)
	ds_write_b128 v69, v[144:147]

; __device__ __forceinline__ void qkt(f32x16& p0, f32x16& p1, const LAS unsigned char* Kt, int r32, int hi, const bf16x8* qr, float init) {
;     f32x16 zi;
; #pragma unroll
;     for (int r = 0; r < 16; ++r) zi[r] = init;
;     const int kt = (int)(uintptr_t)Kt;
;     const int a0 = kt + KSWZ(r32, (0 * 16 + hi * 8) * 2), a1 = kt + KSWZ(r32, (1 * 16 + hi * 8) * 2), a2 = kt + KSWZ(r32, (2 * 16 + hi * 8) * 2), a3 = kt + KSWZ(r32, (3 * 16 + hi * 8) * 2);
;     ...
;     bf16x8 f0, f1, f2, f3, g0, g1, g2, g3, f4, f5, f6, f7, g4, g5, g6, g7;
;     DSR128(f0, a0, 0); DSR128(g0, a0, 8192); DSR128(f1, a1, 0); DSR128(g1, a1, 8192); DSR128(f2, a2, 0); DSR128(g2, a2, 8192); DSR128(f3, a3, 0); DSR128(g3, a3, 8192);
;     asm volatile("s_waitcnt lgkmcnt(0)" : "+v"(f0), "+v"(g0), "+v"(f1), "+v"(g1), "+v"(f2), "+v"(g2), "+v"(f3), "+v"(g3) :: "memory");
;     DSR128(f4, a0, 128); DSR128(g4, a0, 8320); DSR128(f5, a1, 128); DSR128(g5, a1, 8320); DSR128(f6, a2, 128); DSR128(g6, a2, 8320); DSR128(f7, a3, 128); DSR128(g7, a3, 8320);
;     SBAR();
;     p0 = __builtin_amdgcn_mfma_f32_32x32x16_bf16(f0, qr[0], zi, 0, 0, 0); p1 = __builtin_amdgcn_mfma_f32_32x32x16_bf16(g0, qr[0], zi, 0, 0, 0);
;     p0 = __builtin_amdgcn_mfma_f32_32x32x16_bf16(f1, qr[1], p0, 0, 0, 0); p1 = __builtin_amdgcn_mfma_f32_32x32x16_bf16(g1, qr[1], p1, 0, 0, 0);
;     p0 = __builtin_amdgcn_mfma_f32_32x32x16_bf16(f2, qr[2], p0, 0, 0, 0); p1 = __builtin_amdgcn_mfma_f32_32x32x16_bf16(g2, qr[2], p1, 0, 0, 0);
;     p0 = __builtin_amdgcn_mfma_f32_32x32x16_bf16(f3, qr[3], p0, 0, 0, 0); p1 = __builtin_amdgcn_mfma_f32_32x32x16_bf16(g3, qr[3], p1, 0, 0, 0);
;     asm volatile("s_waitcnt lgkmcnt(0)" : "+v"(f4), "+v"(g4), "+v"(f5), "+v"(g5), "+v"(f6), "+v"(g6), "+v"(f7), "+v"(g7) :: "memory");
;     SBAR();
;     p0 = __builtin_amdgcn_mfma_f32_32x32x16_bf16(f4, qr[4], p0, 0, 0, 0); p1 = __builtin_amdgcn_mfma_f32_32x32x16_bf16(g4, qr[4], p1, 0, 0, 0);
;     p0 = __builtin_amdgcn_mfma_f32_32x32x16_bf16(f5, qr[5], p0, 0, 0, 0); p1 = __builtin_amdgcn_mfma_f32_32x32x16_bf16(g5, qr[5], p1, 0, 0, 0);
;     p0 = __builtin_amdgcn_mfma_f32_32x32x16_bf16(f6, qr[6], p0, 0, 0, 0); p1 = __builtin_amdgcn_mfma_f32_32x32x16_bf16(g6, qr[6], p1, 0, 0, 0);
;     p0 = __builtin_amdgcn_mfma_f32_32x32x16_bf16(f7, qr[7], p0, 0, 0, 0); p1 = __builtin_amdgcn_mfma_f32_32x32x16_bf16(g7, qr[7], p1, 0, 0, 0);
;     ...
; }
.LBB0_3525:
	s_and_b32 s0, s10, 0x4000
	s_cmp_gt_i32 s7, s6
	s_cbranch_scc1 .Lmy_ldskip_3
	v_mov_b32_e32 v96, v156
	v_ashrrev_i32_e32 v97, 31, v156
	v_add_u32_e32 v90, 32, v156
	v_lshlrev_b64 v[94:95], 8, v[96:97]
	v_ashrrev_i32_e32 v91, 31, v90
	v_lshl_add_u64 v[88:89], v[152:153], 0, v[94:95]
	v_lshlrev_b64 v[90:91], 8, v[90:91]
	v_lshl_add_u64 v[94:95], v[154:155], 0, v[94:95]
	v_lshl_add_u64 v[92:93], v[152:153], 0, v[90:91]
	global_load_dwordx4 v[132:135], v[88:89], off
	global_load_dwordx4 v[136:139], v[92:93], off
	v_lshl_add_u64 v[88:89], v[154:155], 0, v[90:91]
	global_load_dwordx4 v[140:143], v[94:95], off
	global_load_dwordx4 v[144:147], v[88:89], off
.Lmy_ldskip_3:
	s_add_i32 s12, s0, 0
	s_add_i32 s0, s12, 0xc000
	v_add_u32_e32 v2, s0, v169
	ds_read_b128 v[68:71], v2 offset:0
	ds_read_b128 v[72:75], v2 offset:0x2000
	v_add_u32_e32 v76, s0, v170
	ds_read_b128 v[180:183], v76 offset:0
	ds_read_b128 v[184:187], v76 offset:0x2000
	v_add_u32_e32 v77, s0, v171
	ds_read_b128 v[188:191], v77 offset:0
	ds_read_b128 v[192:195], v77 offset:0x2000
	v_add_u32_e32 v78, s0, v172
	ds_read_b128 v[196:199], v78 offset:0
	ds_read_b128 v[200:203], v78 offset:0x2000
	s_nop 0
	s_waitcnt lgkmcnt(0)
	ds_read_b128 v[204:207], v2 offset:0x80
	ds_read_b128 v[208:211], v2 offset:0x2080
	ds_read_b128 v[212:215], v76 offset:0x80
	ds_read_b128 v[216:219], v76 offset:0x2080
	ds_read_b128 v[220:223], v77 offset:0x80
	ds_read_b128 v[224:227], v77 offset:0x2080
	ds_read_b128 v[228:231], v78 offset:0x80
	ds_read_b128 v[232:235], v78 offset:0x2080
	s_nop 0
	v_mfma_f32_32x32x16_bf16 v[84:99], v[68:71], v[100:103], 0
	v_mfma_f32_32x32x16_bf16 v[68:83], v[72:75], v[100:103], 0
	v_mfma_f32_32x32x16_bf16 v[84:99], v[180:183], v[104:107], v[84:99]
	v_mfma_f32_32x32x16_bf16 v[68:83], v[184:187], v[104:107], v[68:83]
	v_mfma_f32_32x32x16_bf16 v[84:99], v[188:191], v[108:111], v[84:99]
	v_mfma_f32_32x32x16_bf16 v[68:83], v[192:195], v[108:111], v[68:83]
	v_mfma_f32_32x32x16_bf16 v[84:99], v[196:199], v[112:115], v[84:99]
	v_mfma_f32_32x32x16_bf16 v[68:83], v[200:203], v[112:115], v[68:83]
	s_waitcnt lgkmcnt(0)
	v_mfma_f32_32x32x16_bf16 v[84:99], v[204:207], v[116:119], v[84:99]
	s_add_i32 s0, s54, s9
	s_cmp_ge_i32 s0, s95
	v_mfma_f32_32x32x16_bf16 v[68:83], v[208:211], v[116:119], v[68:83]
	v_mfma_f32_32x32x16_bf16 v[84:99], v[212:215], v[120:123], v[84:99]
	v_mfma_f32_32x32x16_bf16 v[68:83], v[216:219], v[120:123], v[68:83]
	v_mfma_f32_32x32x16_bf16 v[84:99], v[220:223], v[124:127], v[84:99]
	v_mfma_f32_32x32x16_bf16 v[68:83], v[224:227], v[124:127], v[68:83]
	v_mfma_f32_32x32x16_bf16 v[84:99], v[228:231], v[128:131], v[84:99]
	v_mfma_f32_32x32x16_bf16 v[68:83], v[232:235], v[128:131], v[68:83]
	s_cbranch_scc1 .LBB0_3527
	ds_read_b32 v180, v176 offset:0xec
	ds_read_b32 v182, v176 offset:0x6c
	ds_read_b32 v181, v176 offset:0xe8
	ds_read_b32 v183, v176 offset:0x68
	ds_read_b32 v184, v176 offset:0xe4
	ds_read_b32 v186, v176 offset:0x64
	ds_read_b32 v185, v176 offset:0xe0
	ds_read_b32 v187, v176 offset:0x60
	ds_read_b32 v188, v176 offset:0xcc
	ds_read_b32 v190, v176 offset:0x4c
	ds_read_b32 v189, v176 offset:0xc8
	ds_read_b32 v191, v176 offset:0x48
	ds_read_b32 v192, v176 offset:0xc4
	ds_read_b32 v194, v176 offset:0x44
	ds_read_b32 v193, v176 offset:0xc0
	ds_read_b32 v195, v176 offset:64
	ds_read_b32 v196, v176 offset:0xac
	ds_read_b32 v198, v176 offset:44
	ds_read_b32 v197, v176 offset:0xa8
	ds_read_b32 v199, v176 offset:40
	ds_read_b32 v200, v176 offset:0xa4
	ds_read_b32 v202, v176 offset:36
	ds_read_b32 v201, v176 offset:0xa0
	ds_read_b32 v203, v176 offset:32
	ds_read_b32 v204, v176 offset:0x8c
	ds_read_b32 v206, v176 offset:12
	ds_read_b32 v205, v176 offset:0x88
	ds_read_b32 v207, v176 offset:8
	ds_read_b32 v208, v176 offset:0x84
	ds_read_b32 v210, v176 offset:4
	ds_read_b32 v209, v176 offset:0x80
	ds_read_b32 v211, v176 offset:0
	s_nop 0
	s_waitcnt lgkmcnt(0)
	s_nop 8
	v_pk_add_f32 v[98:99], v[98:99], v[208:209]
	v_pk_add_f32 v[96:97], v[96:97], v[204:205]
	v_pk_add_f32 v[94:95], v[94:95], v[200:201]
	v_pk_add_f32 v[92:93], v[92:93], v[196:197]
	v_pk_add_f32 v[90:91], v[90:91], v[192:193]
	v_pk_add_f32 v[88:89], v[88:89], v[188:189]
	v_pk_add_f32 v[86:87], v[86:87], v[184:185]
	v_pk_add_f32 v[84:85], v[84:85], v[180:181]
	v_pk_add_f32 v[82:83], v[82:83], v[210:211]
	v_pk_add_f32 v[80:81], v[80:81], v[206:207]
	v_pk_add_f32 v[78:79], v[78:79], v[202:203]
	v_pk_add_f32 v[76:77], v[76:77], v[198:199]
	v_pk_add_f32 v[74:75], v[74:75], v[194:195]
	v_pk_add_f32 v[72:73], v[72:73], v[190:191]
	v_pk_add_f32 v[70:71], v[70:71], v[186:187]
	v_pk_add_f32 v[68:69], v[68:69], v[182:183]

; #define LAS __attribute__((address_space(3)))
; #define SBAR() __builtin_amdgcn_sched_barrier(0)
; __device__ __forceinline__ int v_st(int k, int c) { const int kk = (k & ~0xC) | ((k & 4) << 1) | ((k & 8) >> 1); return ((kk >> 3) * 4 + (c >> 5)) * 512 + ((kk & 7) * 32 + (c & 31)) * 2; }
; __device__ __forceinline__ void pv_tile(f32x16* o, int vb, bf16x8 pa0, bf16x8 pa1, bf16x8 pa2, bf16x8 pa3) {
;     ...
;     PV_D0(0); PV_D0(1); PV_D0(2); PV_D0(3);
;     ...
; }
; __device__ __forceinline__ void pack_p(const f32x16& p0, const f32x16& p1, bf16x8& pa0, bf16x8& pa1, bf16x8& pa2, bf16x8& pa3) {
;     ...
;     PK4(p0, 0, pa0); PK4(p0, 8, pa1); PK4(p1, 0, pa2); PK4(p1, 8, pa3);
;     ...
; }
; __device__ __forceinline__ float half_swap_max(float v) { auto rr = __builtin_amdgcn_permlane32_swap(__float_as_uint(v), __float_as_uint(v), false, false); return fmaxf(__uint_as_float(rr[0]), __uint_as_float(rr[1])); }
; __device__ __forceinline__ float half_swap_sum(float v) { auto rr = __builtin_amdgcn_permlane32_swap(__float_as_uint(v), __float_as_uint(v), false, false); return __uint_as_float(rr[0]) + __uint_as_float(rr[1]); }
; __device__ __forceinline__ void tile_write(const TileStage& T, LAS unsigned char* lds, int kbuf, int vbuf, int sr, int sc) {
;     const int kws = KSWZ(sr, sc * 2);
;     *(LAS bf16x8*)(lds + AT_K + kbuf * SHM_T + kws) = T.k0; *(LAS bf16x8*)(lds + AT_K + kbuf * SHM_T + kws + 32 * 256) = T.k1;
;     *(LAS bf16x8*)(lds + AT_V + vbuf * SHM_T + v_st(sr, sc)) = T.v0; *(LAS bf16x8*)(lds + AT_V + vbuf * SHM_T + v_st(32 + sr, sc)) = T.v1;
; }
; template <int MODE>
; __device__ __forceinline__ void attn_branch(Frame& F, const bf16_t* Kp, const bf16_t* Vp, int j_lo, int j_hi, int sb, const bf16x8* qr, unsigned smask, f32x16* o, float& l_out) {
;     ...
;         float ps = 0.f;
; #pragma unroll
;         for (int r = 0; r < 16; ++r) { C0[r] = __builtin_amdgcn_exp2f(C0[r] - m_reg); C1[r] = __builtin_amdgcn_exp2f(C1[r] - m_reg); ps += C0[r] + C1[r]; }
;         ps = half_swap_sum(ps);
;         l_reg = l_reg * alpha + ps;
;         bf16x8 pa0, pa1, pa2, pa3; pack_p(C0, C1, pa0, pa1, pa2, pa3);
;         if (t + 2 < NT) tile_load(T, Kp, Vp, (j + 2) * 64, sr, sc);
;         SBAR();
;         pv_tile(o, vb0 + vs * SHM_T, pa0, pa1, pa2, pa3);
;         if (t + 2 < NT) tile_write(T, lds, t & 1, vs == 0 ? 2 : vs - 1, sr, sc);
.LBB0_3534:
	v_sub_f32_e32 v84, v84, v2
	v_sub_f32_e32 v68, v68, v2
	v_exp_f32_e32 v157, v84
	v_exp_f32_e32 v180, v68
	v_sub_f32_e32 v68, v85, v2
	v_sub_f32_e32 v69, v69, v2
	v_exp_f32_e32 v68, v68
	v_exp_f32_e32 v181, v69
	v_add_f32_e32 v69, v157, v180
	v_sub_f32_e32 v85, v86, v2
	v_sub_f32_e32 v70, v70, v2
	v_add_f32_e32 v69, 0, v69
	v_add_f32_e32 v84, v68, v181
	v_exp_f32_e32 v86, v85
	v_exp_f32_e32 v182, v70
	v_sub_f32_e32 v70, v87, v2
	v_sub_f32_e32 v71, v71, v2
	v_exp_f32_e32 v70, v70
	v_exp_f32_e32 v87, v71
	v_add_f32_e32 v69, v84, v69
	v_sub_f32_e32 v84, v88, v2
	v_sub_f32_e32 v72, v72, v2
	v_exp_f32_e32 v88, v84
	v_exp_f32_e32 v183, v72
	v_sub_f32_e32 v72, v89, v2
	v_sub_f32_e32 v73, v73, v2
	v_exp_f32_e32 v72, v72
	v_exp_f32_e32 v89, v73
	v_sub_f32_e32 v73, v90, v2
	v_sub_f32_e32 v74, v74, v2
	v_add_f32_e32 v71, v86, v182
	v_exp_f32_e32 v73, v73
	v_exp_f32_e32 v90, v74
	v_sub_f32_e32 v74, v91, v2
	v_sub_f32_e32 v75, v75, v2
	v_add_f32_e32 v69, v71, v69
	v_add_f32_e32 v71, v70, v87
	v_exp_f32_e32 v74, v74
	v_exp_f32_e32 v91, v75
	v_sub_f32_e32 v75, v92, v2
	v_sub_f32_e32 v76, v76, v2
	v_add_f32_e32 v69, v71, v69
	v_add_f32_e32 v71, v88, v183
	v_exp_f32_e32 v75, v75
	v_exp_f32_e32 v76, v76
	v_sub_f32_e32 v84, v93, v2
	v_sub_f32_e32 v77, v77, v2
	v_add_f32_e32 v69, v71, v69
	v_add_f32_e32 v71, v72, v89
	v_exp_f32_e32 v92, v84
	v_exp_f32_e32 v77, v77
	v_sub_f32_e32 v84, v94, v2
	v_sub_f32_e32 v78, v78, v2
	v_add_f32_e32 v69, v71, v69
	v_add_f32_e32 v71, v73, v90
	v_exp_f32_e32 v93, v84
	v_exp_f32_e32 v78, v78
	v_sub_f32_e32 v84, v95, v2
	v_sub_f32_e32 v79, v79, v2
	v_add_f32_e32 v69, v71, v69
	v_add_f32_e32 v71, v74, v91
	v_exp_f32_e32 v94, v84
	v_exp_f32_e32 v79, v79
	v_sub_f32_e32 v84, v96, v2
	v_sub_f32_e32 v80, v80, v2
	v_add_f32_e32 v69, v71, v69
	v_add_f32_e32 v71, v75, v76
	v_exp_f32_e32 v95, v84
	v_exp_f32_e32 v96, v80
	v_sub_f32_e32 v80, v97, v2
	v_sub_f32_e32 v81, v81, v2
	v_add_f32_e32 v69, v71, v69
	v_add_f32_e32 v71, v92, v77
	v_exp_f32_e32 v80, v80
	v_exp_f32_e32 v97, v81
	v_sub_f32_e32 v81, v98, v2
	v_sub_f32_e32 v82, v82, v2
	v_add_f32_e32 v69, v71, v69
	v_add_f32_e32 v71, v93, v78
	v_exp_f32_e32 v81, v81
	v_exp_f32_e32 v98, v82
	v_sub_f32_e32 v82, v99, v2
	v_sub_f32_e32 v83, v83, v2
	v_add_f32_e32 v69, v71, v69
	v_add_f32_e32 v71, v94, v79
	v_exp_f32_e32 v82, v82
	v_exp_f32_e32 v99, v83
	v_add_f32_e32 v69, v71, v69
	v_add_f32_e32 v71, v95, v96
	v_add_f32_e32 v69, v71, v69
	v_add_f32_e32 v71, v80, v97
	v_add_f32_e32 v69, v71, v69
	v_add_f32_e32 v71, v81, v98
	v_add_f32_e32 v69, v71, v69
	v_add_f32_e32 v71, v82, v99
	v_add_f32_e32 v84, v71, v69
	v_mov_b32_e32 v85, v84
	v_cvt_pk_bf16_f32 v68, v157, v68
	v_cvt_pk_bf16_f32 v69, v86, v70
	v_cvt_pk_bf16_f32 v70, v88, v72
	v_cvt_pk_bf16_f32 v71, v73, v74
	v_cvt_pk_bf16_f32 v72, v75, v92
	v_cvt_pk_bf16_f32 v73, v93, v94
	v_cvt_pk_bf16_f32 v74, v95, v80
	v_cvt_pk_bf16_f32 v75, v81, v82
	v_cvt_pk_bf16_f32 v80, v180, v181
	v_cvt_pk_bf16_f32 v81, v182, v87
	v_cvt_pk_bf16_f32 v82, v183, v89
	v_cvt_pk_bf16_f32 v83, v90, v91
	v_cvt_pk_bf16_f32 v76, v76, v77
	v_cvt_pk_bf16_f32 v77, v78, v79
	v_cvt_pk_bf16_f32 v78, v96, v97
	v_cvt_pk_bf16_f32 v79, v98, v99
	s_cmp_le_i32 s7, s6
	s_nop 0
	v_permlane32_swap_b32_e32 v84, v85
	v_permlane32_swap_b32_e32 v68, v70
	v_permlane32_swap_b32_e32 v69, v71
	v_permlane32_swap_b32_e32 v72, v74
	v_permlane32_swap_b32_e32 v73, v75
	v_permlane32_swap_b32_e32 v80, v82
	v_permlane32_swap_b32_e32 v81, v83
	v_permlane32_swap_b32_e32 v76, v78
	s_cselect_b64 s[0:1], -1, 0
	s_cmp_gt_i32 s7, s6
	v_permlane32_swap_b32_e32 v77, v79
	s_cbranch_scc1 .LBB0_3536
.LBB0_3536:
	s_lshl_b32 s13, s11, 14
	v_add_u32_e32 v98, s13, v175
	ds_read_b64_tr_b16 v[86:87], v98 offset:0
	ds_read_b64_tr_b16 v[88:89], v98 offset:0x800
	ds_read_b64_tr_b16 v[90:91], v98 offset:0x1000
	ds_read_b64_tr_b16 v[92:93], v98 offset:0x1800
	ds_read_b64_tr_b16 v[94:95], v98 offset:0x2000
	ds_read_b64_tr_b16 v[96:97], v98 offset:0x2800
	ds_read_b64_tr_b16 v[180:181], v98 offset:0x3000
	ds_read_b64_tr_b16 v[182:183], v98 offset:0x3800
	s_waitcnt lgkmcnt(0)
	s_nop 0
	v_mfma_f32_32x32x16_bf16 v[52:67], v[68:71], v[86:89], v[52:67]
	ds_read_b64_tr_b16 v[86:87], v98 offset:0x200
	ds_read_b64_tr_b16 v[88:89], v98 offset:0xa00
	v_mfma_f32_32x32x16_bf16 v[52:67], v[72:75], v[90:93], v[52:67]
	ds_read_b64_tr_b16 v[90:91], v98 offset:0x1200
	ds_read_b64_tr_b16 v[92:93], v98 offset:0x1a00
	v_mfma_f32_32x32x16_bf16 v[52:67], v[80:83], v[94:97], v[52:67]
	ds_read_b64_tr_b16 v[94:95], v98 offset:0x2200
	ds_read_b64_tr_b16 v[96:97], v98 offset:0x2a00
	v_mfma_f32_32x32x16_bf16 v[52:67], v[76:79], v[180:183], v[52:67]
	ds_read_b64_tr_b16 v[180:181], v98 offset:0x3200
	ds_read_b64_tr_b16 v[182:183], v98 offset:0x3a00
	s_waitcnt lgkmcnt(0)
	v_mfma_f32_32x32x16_bf16 v[36:51], v[68:71], v[86:89], v[36:51]
	ds_read_b64_tr_b16 v[86:87], v98 offset:0x400
	ds_read_b64_tr_b16 v[88:89], v98 offset:0xc00
	v_mfma_f32_32x32x16_bf16 v[36:51], v[72:75], v[90:93], v[36:51]
	ds_read_b64_tr_b16 v[90:91], v98 offset:0x1400
	ds_read_b64_tr_b16 v[92:93], v98 offset:0x1c00
	v_mfma_f32_32x32x16_bf16 v[36:51], v[80:83], v[94:97], v[36:51]
	ds_read_b64_tr_b16 v[94:95], v98 offset:0x2400
	ds_read_b64_tr_b16 v[96:97], v98 offset:0x2c00
	v_mfma_f32_32x32x16_bf16 v[36:51], v[76:79], v[180:183], v[36:51]
	ds_read_b64_tr_b16 v[180:181], v98 offset:0x3400
	ds_read_b64_tr_b16 v[182:183], v98 offset:0x3c00
	s_waitcnt lgkmcnt(0)
	v_mfma_f32_32x32x16_bf16 v[20:35], v[68:71], v[86:89], v[20:35]
	ds_read_b64_tr_b16 v[86:87], v98 offset:0x600
	ds_read_b64_tr_b16 v[88:89], v98 offset:0xe00
	v_mfma_f32_32x32x16_bf16 v[20:35], v[72:75], v[90:93], v[20:35]
	ds_read_b64_tr_b16 v[90:91], v98 offset:0x1600
	ds_read_b64_tr_b16 v[92:93], v98 offset:0x1e00
	v_mfma_f32_32x32x16_bf16 v[20:35], v[80:83], v[94:97], v[20:35]
	ds_read_b64_tr_b16 v[94:95], v98 offset:0x2600
	ds_read_b64_tr_b16 v[96:97], v98 offset:0x2e00
	v_mfma_f32_32x32x16_bf16 v[20:35], v[76:79], v[180:183], v[20:35]
	ds_read_b64_tr_b16 v[180:181], v98 offset:0x3600
	ds_read_b64_tr_b16 v[182:183], v98 offset:0x3e00
	s_waitcnt lgkmcnt(0)
	v_mfma_f32_32x32x16_bf16 v[4:19], v[68:71], v[86:89], v[4:19]
	s_andn2_b64 vcc, exec, s[0:1]
	v_mfma_f32_32x32x16_bf16 v[4:19], v[72:75], v[90:93], v[4:19]
	v_mfma_f32_32x32x16_bf16 v[4:19], v[80:83], v[94:97], v[4:19]
	v_mfma_f32_32x32x16_bf16 v[4:19], v[76:79], v[180:183], v[4:19]
	s_cbranch_vccnz .LBB0_3538
	s_addk_i32 s13, 0xc000
	s_cmp_lg_u32 s11, 0
	s_cselect_b32 s0, s13, 0x8000
	v_add_u32_e32 v68, s0, v167
	v_add3_u32 v70, s12, v159, v161
	v_add3_u32 v69, v68, v168, v166
	v_add3_u32 v68, v68, v165, v166
	s_waitcnt vmcnt(3)
	ds_write_b128 v70, v[132:135] offset:49152
	s_waitcnt vmcnt(2)
	ds_write_b128 v70, v[136:139] offset:57344
	s_waitcnt vmcnt(1)
	ds_write_b128 v68, v[140:143]
	s_waitcnt vmcnt(0)
	ds_write_b128 v69, v[144:147]
